# v52 + LRU2: pass-1 x LDS reads issued per half up front, 16th gate-weight fragment hoisted, no vmcnt(0) behind the AD stores
# speedup vs baseline: 1.0228x; 1.0051x over previous
; __device__ __forceinline__ float log_sigmoid(float x) { return fminf(x, 0.f) - log1pf(expf(-fabsf(x))); }
; __device__ __forceinline__ void lru_gate_consts(LruGateC& gc, const Args& a, int l, int lane, int wave) { const int k = wave & 3, dir = wave >> 2;
; #pragma unroll
;     for (int ct = 0; ct < 2; ++ct) { const int ch = 64 * k + 32 * ct + (lane & 31); gc.ba[ct] = a.lru_ba[(l * 2 + dir) * 256 + ch]; gc.bx[ct] = a.lru_bx[(l * 2 + dir) * 256 + ch]; gc.lsl[ct] = 8.0f * log_sigmoid(a.lru_lam[(l * 2 + dir) * 256 + ch]); } }
.LBB0_549:
	v_readlane_b32 s0, v254, 22
	v_mov_b32_e32 v2, v212
	v_readlane_b32 s1, v254, 23
	s_andn2_b64 vcc, exec, s[0:1]
	v_readfirstlane_b32 s0, v2
	s_cbranch_vccnz .LBB0_576
	v_readlane_b32 s2, v253, 41
	s_lshl_b32 s1, s2, 9
	s_and_b32 s7, s0, 0xffffff00
	s_and_b32 s6, s0, 0xc0
	s_add_i32 s7, s7, s1
	v_and_b32_e32 v3, 31, v2
	s_or_b32 s1, s7, s6
	v_or_b32_e32 v4, s1, v3
	v_ashrrev_i32_e32 v5, 31, v4
	v_readlane_b32 s4, v253, 2
	v_lshlrev_b64 v[4:5], 2, v[4:5]
	v_readlane_b32 s5, v253, 3
	v_readlane_b32 s6, v253, 4
	v_readlane_b32 s7, v253, 5
	v_lshl_add_u64 v[6:7], s[4:5], 0, v[4:5]
	global_load_dword v0, v[6:7], off
	global_load_dword v8, v[6:7], off offset:128
	v_readlane_b32 s8, v253, 6
	v_readlane_b32 s9, v253, 7
	v_readlane_b32 s10, v253, 8
	v_readlane_b32 s11, v253, 9
	v_readlane_b32 s12, v253, 10
	v_readlane_b32 s13, v253, 11
	v_readlane_b32 s14, v253, 12
	v_readlane_b32 s15, v253, 13
	v_readlane_b32 s16, v253, 14
	v_readlane_b32 s17, v253, 15
	v_readlane_b32 s18, v253, 16
	v_readlane_b32 s19, v253, 17
	v_readlane_b32 s4, v253, 25
	v_readlane_b32 s14, v253, 35
	v_readlane_b32 s15, v253, 36
	v_readlane_b32 s18, v253, 39
	v_readlane_b32 s19, v253, 40
	v_lshl_add_u64 v[6:7], s[14:15], 0, v[4:5]
	v_readlane_b32 s6, v253, 27
	v_lshl_add_u64 v[4:5], s[18:19], 0, v[4:5]
	global_load_dword v136, v[6:7], off
	global_load_dword v137, v[6:7], off offset:128
	global_load_dword v138, v[4:5], off
	global_load_dword v139, v[4:5], off offset:128
	v_readlane_b32 s8, v253, 29
	s_lshl_b32 s1, s2, 12
	v_readlane_b32 s7, v253, 28
	v_readlane_b32 s9, v253, 30
	s_add_u32 s6, s8, s1
	v_readlane_b32 s3, v253, 42
	s_addc_u32 s7, s9, 0
	s_lshl_b32 s1, s2, 1
	s_bfe_u32 s8, s0, 0x20006
	s_ashr_i32 s0, s0, 8
	v_readlane_b32 s10, v253, 31
	v_readlane_b32 s11, v253, 32
	v_ashrrev_i32_e32 v142, 5, v2
	v_readlane_b32 s4, v255, 49
	v_ashrrev_i32_e32 v84, 8, v2
	v_ashrrev_i32_e32 v85, 31, v84
	v_readlane_b32 s5, v253, 26
	v_readlane_b32 s12, v253, 33
	v_readlane_b32 s13, v253, 34
	v_readlane_b32 s16, v253, 37
	v_readlane_b32 s17, v253, 38
	s_waitcnt vmcnt(5)
	v_mul_f32_e64 v5, |v0|, s35
	s_waitcnt vmcnt(4)
	v_mul_f32_e64 v7, |v8|, s35
	v_fma_f32 v9, |v0|, s35, -v5
	v_rndne_f32_e32 v10, v5
	v_fma_f32 v11, |v8|, s35, -v7
	v_rndne_f32_e32 v12, v7
	v_fma_f32 v9, |v0|, s37, v9
	v_sub_f32_e32 v5, v5, v10
	v_fma_f32 v11, |v8|, s37, v11
	v_sub_f32_e32 v7, v7, v12
	v_add_f32_e32 v5, v5, v9
	v_cvt_i32_f32_e32 v10, v10
	v_add_f32_e32 v7, v7, v11
	v_exp_f32_e32 v5, v5
	v_cvt_i32_f32_e32 v12, v12
	v_exp_f32_e32 v7, v7
	v_max_f32_e32 v4, v0, v0
	v_min_f32_e32 v9, 0, v4
	v_ldexp_f32 v4, v5, v10
	v_cmp_ngt_f32_e64 vcc, |v0|, s38
	v_ldexp_f32 v5, v7, v12
	v_max_f32_e32 v6, v8, v8
	v_cndmask_b32_e32 v4, 0, v4, vcc
	v_cmp_ngt_f32_e64 vcc, |v8|, s38
	v_min_f32_e32 v6, 0, v6
	s_nop 0
	v_cndmask_b32_e32 v5, 0, v5, vcc
	v_cmp_nlt_f32_e64 vcc, |v0|, s39
	s_nop 1
	v_cndmask_b32_e32 v0, v219, v4, vcc
	v_cmp_nlt_f32_e64 vcc, |v8|, s39
	v_add_f32_e32 v8, 1.0, v0
	v_frexp_mant_f32_e32 v12, v8
	v_cndmask_b32_e32 v7, v219, v5, vcc
	v_cvt_f64_f32_e32 v[4:5], v8
	v_add_f32_e32 v11, -1.0, v8
	v_frexp_exp_i32_f64_e32 v4, v[4:5]
	v_cmp_gt_f32_e32 vcc, s48, v12
	v_sub_f32_e32 v14, v11, v8
	v_sub_f32_e32 v11, v0, v11
	v_subbrev_co_u32_e32 v4, vcc, 0, v4, vcc
	v_add_f32_e32 v14, 1.0, v14
	v_sub_u32_e32 v12, 0, v4
	v_add_f32_e32 v11, v11, v14
	v_cvt_f32_i32_e32 v4, v4
	v_ldexp_f32 v8, v8, v12
	v_ldexp_f32 v11, v11, v12
	v_add_f32_e32 v12, -1.0, v8
	v_add_f32_e32 v14, 1.0, v8
	v_add_f32_e32 v15, 1.0, v12
	v_add_f32_e32 v16, -1.0, v14
	v_sub_f32_e32 v15, v8, v15
	v_sub_f32_e32 v8, v8, v16
	v_mul_f32_e32 v16, 0x3f317218, v4
	v_add_f32_e32 v15, v11, v15
	v_add_f32_e32 v8, v11, v8
	v_fma_f32 v11, v4, s49, -v16
	v_add_f32_e32 v17, v12, v15
	v_add_f32_e32 v18, v14, v8
	v_fmac_f32_e32 v11, 0xb102e308, v4
	v_sub_f32_e32 v4, v12, v17
	v_sub_f32_e32 v12, v14, v18
	v_rcp_f32_e32 v14, v18
	v_add_f32_e32 v19, v16, v11
	v_add_f32_e32 v8, v8, v12
	v_sub_f32_e32 v12, v19, v16
	v_sub_f32_e32 v11, v11, v12
	v_mul_f32_e32 v12, v17, v14
	v_add_f32_e32 v4, v15, v4
	v_mul_f32_e32 v15, v18, v12
	v_fma_f32 v16, v12, v18, -v15
	v_fmac_f32_e32 v16, v12, v8
	v_add_f32_e32 v20, v15, v16
	v_sub_f32_e32 v21, v17, v20
	v_sub_f32_e32 v15, v20, v15
	v_sub_f32_e32 v17, v17, v21
	v_sub_f32_e32 v15, v15, v16
	v_sub_f32_e32 v16, v17, v20
	v_add_f32_e32 v4, v4, v16
	v_add_f32_e32 v4, v15, v4
	v_add_f32_e32 v15, v21, v4
	v_mul_f32_e32 v16, v14, v15
	v_sub_f32_e32 v17, v21, v15
	v_mul_f32_e32 v20, v18, v16
	v_add_f32_e32 v4, v4, v17
	v_add_f32_e32 v17, v12, v16
	v_fma_f32 v18, v16, v18, -v20
	v_sub_f32_e32 v12, v17, v12
	v_fmac_f32_e32 v18, v16, v8
	v_sub_f32_e32 v8, v16, v12
	v_add_f32_e32 v12, v20, v18
	v_sub_f32_e32 v16, v12, v20
	v_sub_f32_e32 v20, v15, v12
	v_sub_f32_e32 v15, v15, v20
	v_sub_f32_e32 v12, v15, v12
	v_sub_f32_e32 v16, v16, v18
	v_add_f32_e32 v4, v4, v12
	v_add_f32_e32 v4, v16, v4
	v_add_f32_e32 v4, v20, v4
	v_mul_f32_e32 v4, v14, v4
	v_add_f32_e32 v4, v8, v4
	v_add_f32_e32 v8, v17, v4
	v_mul_f32_e32 v12, v8, v8
	v_fmamk_f32 v16, v12, 0x3e9b6dac, v217
	v_sub_f32_e32 v14, v8, v17
	v_ldexp_f32 v15, v8, 1
	v_mul_f32_e32 v8, v8, v12
	v_fmaak_f32 v12, v12, v16, 0x3f2aaada
	v_mul_f32_e32 v8, v8, v12
	v_add_f32_e32 v12, v15, v8
	v_sub_f32_e32 v4, v4, v14
	v_sub_f32_e32 v14, v12, v15
	v_ldexp_f32 v4, v4, 1
	v_sub_f32_e32 v8, v8, v14
	v_add_f32_e32 v4, v4, v8
	v_add_f32_e32 v8, v12, v4
	v_sub_f32_e32 v12, v8, v12
	v_add_f32_e32 v14, v19, v8
	v_sub_f32_e32 v4, v4, v12
	v_sub_f32_e32 v12, v14, v19
	v_sub_f32_e32 v15, v14, v12
	v_sub_f32_e32 v8, v8, v12
	v_add_f32_e32 v12, v11, v4
	v_sub_f32_e32 v15, v19, v15
	v_sub_f32_e32 v16, v12, v11
; #define LAS __attribute__((address_space(3)))
; __device__ __forceinline__ void lru_gate_consts(LruGateC& gc, const Args& a, int l, int lane, int wave) { const int k = wave & 3, dir = wave >> 2;
; #pragma unroll
;     for (int ct = 0; ct < 2; ++ct) { const int ch = 64 * k + 32 * ct + (lane & 31); gc.ba[ct] = a.lru_ba[(l * 2 + dir) * 256 + ch]; gc.bx[ct] = a.lru_bx[(l * 2 + dir) * 256 + ch]; gc.lsl[ct] = 8.0f * log_sigmoid(a.lru_lam[(l * 2 + dir) * 256 + ch]); } }
; __device__ __forceinline__ void lru_pass1_unit(int cu4, const Args& a, int l, const bf16* LX, const bf16* WLRU, h2* AD, float2* LCS4, lds_t* lds, int tid, int lane, int wave, const LruGateC& gc) {
;     const int cu = cu4 >> 2, rt0 = cu4 & 3;
;     const int b = cu < 256 ? cu >> 5 : (cu - 256) >> 1, c = cu < 256 ? cu & 31 : 32 + ((cu - 256) & 1);
;     const int m0 = chunk_row0(b, c), ms = c < 32 ? b * SEQ : ML + b * CTXL, me = ms + (c < 32 ? SEQ : CTXL);
;     lds_t* XR = lds; LAS h2* ADL = (LAS h2*)(lds + 128 * LR_LDX);
;     { const int w8 = (tid & 31) * 8, tr = tid >> 5; float cw[4][8], cb[8];
; #pragma unroll
;         for (int j = 0; j < 4; ++j)
; #pragma unroll
;             for (int e = 0; e < 8; ++e) cw[j][e] = a.conv_w[(size_t)l * 1024 + j * 256 + w8 + e];
; #pragma unroll
;         for (int e = 0; e < 8; ++e) cb[e] = a.conv_b[l * 256 + w8 + e];
;         for (int i = 0; i < 2; ++i) { const int t = 32 * rt0 + tr + 16 * i; float acc[8];
; #pragma unroll
;             for (int e = 0; e < 8; ++e) acc[e] = cb[e];
; #pragma unroll
;             for (int j = 0; j < 4; ++j) { const int m = m0 + t + j - 2;
;                 if (m >= ms && m < me) { const v4u xv = *(const v4u*)(LX + (size_t)m * 256 + w8);
; #pragma unroll
;                     for (int e = 0; e < 4; ++e) { acc[2 * e] += bflo(xv[e]) * cw[j][2 * e]; acc[2 * e + 1] += bfhi(xv[e]) * cw[j][2 * e + 1]; } } }
;             v4u ow;
; #pragma unroll
;             for (int e = 0; e < 4; ++e) ow[e] = pk2(acc[2 * e], acc[2 * e + 1]);
;             *(LAS v4u*)(XR + (t & 31) * LR_LDX + w8 * 2) = ow; } }
;     __syncthreads();
;     const int k = wave & 3, dir = wave >> 2;
;     const float (&ba)[2] = gc.ba; const float (&bx)[2] = gc.bx; const float (&lsl)[2] = gc.lsl;
;     float At = 1.f, Ht = 0.f;
;     for (int rt = rt0; rt < rt0 + 1; ++rt) {
;         bf16x8 af[4];
; #pragma unroll
	v_add_f32_e32 v8, v8, v15
	v_sub_f32_e32 v15, v12, v16
	v_sub_f32_e32 v4, v4, v16
	v_sub_f32_e32 v11, v11, v15
	v_add_f32_e32 v8, v12, v8
	v_add_f32_e32 v4, v4, v11
	v_add_f32_e32 v11, v14, v8
	v_sub_f32_e32 v12, v11, v14
	v_sub_f32_e32 v8, v8, v12
	v_add_f32_e32 v4, v4, v8
	v_add_f32_e32 v4, v11, v4
	v_cmp_neq_f32_e32 vcc, s46, v0
	v_add_f32_e32 v10, 1.0, v7
	v_add_f32_e32 v13, -1.0, v10
	v_cndmask_b32_e32 v4, v219, v4, vcc
	v_cmp_lt_f32_e64 vcc, |v0|, s50
	v_sub_f32_e32 v5, v13, v10
	v_frexp_mant_f32_e32 v8, v10
	v_cndmask_b32_e32 v0, v4, v0, vcc
	v_sub_f32_e32 v0, v9, v0
	v_mul_f32_e32 v140, 0x41000000, v0
	v_add_f32_e32 v0, 1.0, v5
	v_sub_f32_e32 v4, v7, v13
	v_add_f32_e32 v0, v4, v0
	v_cvt_f64_f32_e32 v[4:5], v10
	v_frexp_exp_i32_f64_e32 v4, v[4:5]
	v_cmp_gt_f32_e32 vcc, s48, v8
	s_nop 1
	v_subbrev_co_u32_e32 v4, vcc, 0, v4, vcc
	v_sub_u32_e32 v5, 0, v4
	v_ldexp_f32 v8, v10, v5
	v_ldexp_f32 v0, v0, v5
	v_add_f32_e32 v5, -1.0, v8
	v_add_f32_e32 v11, 1.0, v8
	v_add_f32_e32 v9, 1.0, v5
	v_add_f32_e32 v12, -1.0, v11
	v_sub_f32_e32 v9, v8, v9
	v_sub_f32_e32 v8, v8, v12
	v_add_f32_e32 v9, v0, v9
	v_add_f32_e32 v0, v0, v8
	v_add_f32_e32 v8, v11, v0
	v_rcp_f32_e32 v12, v8
	v_add_f32_e32 v10, v5, v9
	v_sub_f32_e32 v5, v5, v10
	v_add_f32_e32 v5, v9, v5
	v_sub_f32_e32 v9, v11, v8
	v_add_f32_e32 v0, v0, v9
	v_mul_f32_e32 v9, v10, v12
	v_mul_f32_e32 v11, v8, v9
	v_fma_f32 v13, v9, v8, -v11
	v_fmac_f32_e32 v13, v9, v0
	v_add_f32_e32 v14, v11, v13
	v_sub_f32_e32 v15, v10, v14
	v_sub_f32_e32 v10, v10, v15
	v_sub_f32_e32 v11, v14, v11
	v_sub_f32_e32 v10, v10, v14
	v_add_f32_e32 v5, v5, v10
	v_sub_f32_e32 v10, v11, v13
	v_add_f32_e32 v5, v10, v5
	v_add_f32_e32 v10, v15, v5
	v_mul_f32_e32 v11, v12, v10
	v_mul_f32_e32 v13, v8, v11
	v_fma_f32 v8, v11, v8, -v13
	v_fmac_f32_e32 v8, v11, v0
	v_sub_f32_e32 v0, v15, v10
	v_add_f32_e32 v0, v5, v0
	v_add_f32_e32 v5, v13, v8
	v_sub_f32_e32 v14, v10, v5
	v_sub_f32_e32 v10, v10, v14
	v_sub_f32_e32 v13, v5, v13
	v_sub_f32_e32 v5, v10, v5
	v_add_f32_e32 v0, v0, v5
	v_sub_f32_e32 v5, v13, v8
	v_cvt_f32_i32_e32 v4, v4
	v_add_f32_e32 v0, v5, v0
	v_add_f32_e32 v5, v9, v11
	v_add_f32_e32 v0, v14, v0
	v_sub_f32_e32 v8, v5, v9
	v_mul_f32_e32 v0, v12, v0
	v_sub_f32_e32 v8, v11, v8
	v_add_f32_e32 v0, v8, v0
	v_mul_f32_e32 v11, 0x3f317218, v4
	v_add_f32_e32 v8, v5, v0
	v_fma_f32 v12, v4, s49, -v11
	v_mul_f32_e32 v9, v8, v8
	v_fmac_f32_e32 v12, 0xb102e308, v4
	v_sub_f32_e32 v4, v8, v5
	v_fmamk_f32 v10, v9, 0x3e9b6dac, v217
	v_sub_f32_e32 v0, v0, v4
	v_add_f32_e32 v4, v11, v12
	v_fmaak_f32 v10, v9, v10, 0x3f2aaada
	v_sub_f32_e32 v5, v4, v11
	v_ldexp_f32 v11, v8, 1
	v_mul_f32_e32 v8, v8, v9
	v_mul_f32_e32 v8, v8, v10
	v_add_f32_e32 v9, v11, v8
	v_sub_f32_e32 v10, v9, v11
	v_ldexp_f32 v0, v0, 1
	v_sub_f32_e32 v8, v8, v10
	v_add_f32_e32 v0, v0, v8
	v_add_f32_e32 v8, v9, v0
	v_sub_f32_e32 v9, v8, v9
	v_sub_f32_e32 v0, v0, v9
	v_add_f32_e32 v9, v4, v8
	v_sub_f32_e32 v10, v9, v4
	v_sub_f32_e32 v11, v9, v10
	v_sub_f32_e32 v5, v12, v5
	v_sub_f32_e32 v4, v4, v11
	v_sub_f32_e32 v8, v8, v10
	v_add_f32_e32 v4, v8, v4
	v_add_f32_e32 v8, v5, v0
	v_sub_f32_e32 v10, v8, v5
	v_sub_f32_e32 v11, v8, v10
	v_sub_f32_e32 v5, v5, v11
	v_sub_f32_e32 v0, v0, v10
	v_add_f32_e32 v4, v8, v4
	v_add_f32_e32 v0, v0, v5
	v_add_f32_e32 v5, v9, v4
	v_sub_f32_e32 v8, v5, v9
	v_sub_f32_e32 v4, v4, v8
	v_add_f32_e32 v0, v0, v4
	v_add_f32_e32 v0, v5, v0
	v_cmp_neq_f32_e32 vcc, s46, v7
	v_lshrrev_b32_e32 v10, 3, v2
	v_and_b32_e32 v144, 4, v10
	v_cndmask_b32_e32 v0, v219, v0, vcc
	v_cmp_lt_f32_e64 vcc, |v7|, s50
	v_and_b32_e32 v10, 0x3fffff00, v2
	v_mov_b32_e32 v12, 2
	v_cndmask_b32_e32 v0, v0, v7, vcc
	v_sub_f32_e32 v0, v6, v0
	v_mul_f32_e32 v141, 0x41000000, v0
	v_lshlrev_b32_e32 v0, 3, v2
	v_and_b32_e32 v4, 0xf8, v0
	v_lshlrev_b32_e32 v0, 2, v4
	v_lshl_add_u64 v[50:51], s[6:7], 0, v[0:1]
	v_lshl_or_b32 v0, s2, 8, v4
	v_readlane_b32 s2, v252, 39
	s_add_i32 s6, s0, s1
	v_lshl_add_u64 v[52:53], v[0:1], 2, s[10:11]
	v_lshlrev_b32_e32 v0, 1, v4
	v_readlane_b32 s3, v252, 40
	s_ashr_i32 s7, s6, 31
	v_add_u32_e32 v143, 0, v0
	v_lshl_add_u64 v[54:55], s[2:3], 0, v[0:1]
	v_and_b32_e32 v0, 31, v142
	s_lshl_b64 s[6:7], s[6:7], 9
	s_lshl_b32 s1, s8, 6
	v_mul_u32_u24_e32 v8, 0x210, v0
	s_or_b32 s6, s6, s1
	v_lshrrev_b32_e32 v0, 1, v2
	v_readlane_b32 s2, v252, 4
; #define LAS __attribute__((address_space(3)))
; __device__ __forceinline__ unsigned pk2(float lo, float hi) { return f2bf(lo) | (f2bf(hi) << 16); }
; __device__ __forceinline__ void lru_pass1_unit(int cu4, const Args& a, int l, const bf16* LX, const bf16* WLRU, h2* AD, float2* LCS4, lds_t* lds, int tid, int lane, int wave, const LruGateC& gc) {
;     ...
;     const int m0 = chunk_row0(b, c), ms = c < 32 ? b * SEQ : ML + b * CTXL, me = ms + (c < 32 ? SEQ : CTXL);
;     lds_t* XR = lds; LAS h2* ADL = (LAS h2*)(lds + 128 * LR_LDX);
;     { const int w8 = (tid & 31) * 8, tr = tid >> 5; float cw[4][8], cb[8];
; #pragma unroll
;         for (int j = 0; j < 4; ++j)
; #pragma unroll
;             for (int e = 0; e < 8; ++e) cw[j][e] = a.conv_w[(size_t)l * 1024 + j * 256 + w8 + e];
; #pragma unroll
;         for (int e = 0; e < 8; ++e) cb[e] = a.conv_b[l * 256 + w8 + e];
;         for (int i = 0; i < 2; ++i) { const int t = 32 * rt0 + tr + 16 * i; float acc[8];
; #pragma unroll
;             for (int e = 0; e < 8; ++e) acc[e] = cb[e];
; #pragma unroll
;             for (int j = 0; j < 4; ++j) { const int m = m0 + t + j - 2;
;                 if (m >= ms && m < me) { const v4u xv = *(const v4u*)(LX + (size_t)m * 256 + w8);
; #pragma unroll
;                     for (int e = 0; e < 4; ++e) { acc[2 * e] += bflo(xv[e]) * cw[j][2 * e]; acc[2 * e + 1] += bfhi(xv[e]) * cw[j][2 * e + 1]; } } }
;             v4u ow;
; #pragma unroll
;             for (int e = 0; e < 4; ++e) ow[e] = pk2(acc[2 * e], acc[2 * e + 1]);
;             *(LAS v4u*)(XR + (t & 31) * LR_LDX + w8 * 2) = ow; } }
;     __syncthreads();
;     const int k = wave & 3, dir = wave >> 2;
;     const float (&ba)[2] = gc.ba; const float (&bx)[2] = gc.bx; const float (&lsl)[2] = gc.lsl;
;     float At = 1.f, Ht = 0.f;
;     for (int rt = rt0; rt < rt0 + 1; ++rt) {
;         bf16x8 af[4];
; #pragma unroll
;         for (int ks = 0; ks < 4; ++ks) af[ks] = *(const LAS bf16x8*)(XR + (lane & 31) * LR_LDX + (64 * k + 16 * ks + 8 * (lane >> 5)) * 2);
; #pragma unroll
;         for (int ct = 0; ct < 2; ++ct) { f32x16 ga = {}, gx = {};
; #pragma unroll
;             for (int ks = 0; ks < 4; ++ks) { const bf16* wb = WLRU + (((size_t)(l * 2 + dir) * 2 * 4 + k) * 64 + 32 * ct + (lane & 31)) * 64 + 16 * ks + 8 * (lane >> 5);
	v_or_b32_e32 v9, s1, v3
	s_lshl_b32 s1, s0, 10
	v_and_b32_e32 v0, 16, v0
	v_readlane_b32 s3, v252, 5
	s_add_i32 s10, s4, s1
	s_ashr_i32 s1, s0, 31
	v_or_b32_e32 v4, s6, v3
	v_mov_b32_e32 v5, s7
	v_lshl_add_u64 v[6:7], s[2:3], 0, v[0:1]
	s_lshl_b64 s[0:1], s[0:1], 10
	v_readlane_b32 s2, v252, 43
	v_readlane_b32 s3, v252, 44
	s_add_u32 s0, s2, s0
	v_lshlrev_b64 v[4:5], 7, v[4:5]
	s_addc_u32 s1, s3, s1
	v_lshl_add_u64 v[56:57], v[6:7], 0, v[4:5]
	v_lshlrev_b32_e32 v4, 2, v9
	v_mov_b32_e32 v5, v1
	v_lshl_add_u64 v[66:67], s[0:1], 0, v[4:5]
	s_mov_b64 s[0:1], 0x9000
	v_lshl_add_u64 v[70:71], v[56:57], 0, s[0:1]
	s_mov_b64 s[0:1], 0x1020
	v_lshl_add_u64 v[72:73], v[56:57], 0, s[0:1]
	s_mov_b64 s[0:1], 0x9020
	v_lshl_add_u64 v[74:75], v[56:57], 0, s[0:1]
	s_mov_b64 s[0:1], 0x1040
	s_lshl_b32 s8, s8, 7
	v_lshl_add_u64 v[76:77], v[56:57], 0, s[0:1]
	s_mov_b64 s[0:1], 0x9040
	v_lshlrev_b32_e32 v10, 2, v10
	v_lshlrev_b32_sdwa v12, v12, v2 dst_sel:DWORD dst_unused:UNUSED_PAD src0_sel:DWORD src1_sel:BYTE_0
	s_add_i32 s8, s8, 0
	v_lshl_add_u64 v[78:79], v[56:57], 0, s[0:1]
	s_mov_b64 s[0:1], 0x1060
	v_bfe_u32 v11, v2, 3, 3
	v_add3_u32 v145, s4, v10, v12
	v_mov_b32_e32 v10, s8
	s_mov_b64 s[8:9], 0x8020
	v_lshl_add_u64 v[80:81], v[56:57], 0, s[0:1]
	s_mov_b64 s[0:1], 0x9060
	v_mad_u32_u24 v10, v3, s51, v10
	v_lshl_add_u64 v[60:61], v[56:57], 0, s[8:9]
	s_mov_b64 s[8:9], 0x8040
	v_or_b32_e32 v148, 1, v144
	v_or_b32_e32 v149, 2, v144
	v_or_b32_e32 v150, 3, v11
	v_or_b32_e32 v152, 8, v144
	v_or_b32_e32 v153, 9, v144
	v_or_b32_e32 v154, 10, v144
	v_or_b32_e32 v155, 11, v11
	v_or_b32_e32 v157, 16, v144
	v_or_b32_e32 v158, 17, v144
	v_or_b32_e32 v159, 18, v144
	v_or_b32_e32 v160, 19, v11
	v_or_b32_e32 v162, 24, v144
	v_or_b32_e32 v163, 25, v144
	v_or_b32_e32 v164, 26, v144
	v_or_b32_e32 v165, 27, v11
	v_lshl_add_u64 v[82:83], v[56:57], 0, s[0:1]
	v_mov_b32_e32 v3, 3
	v_readlane_b32 s0, v252, 28
	v_cmp_lt_u32_e64 s[6:7], s34, v2
	v_lshl_add_u64 v[62:63], v[56:57], 0, s[8:9]
	s_mov_b64 s[8:9], 0x8060
	v_lshl_add_u32 v146, v9, 1, 0
	v_add_u32_e32 v6, s10, v4
	v_lshlrev_b32_e32 v4, 11, v144
	v_lshlrev_b32_e32 v5, 11, v148
	v_lshlrev_b32_e32 v7, 11, v149
	v_lshlrev_b32_e32 v9, 11, v150
	v_lshlrev_b32_e32 v12, 11, v152
	v_lshlrev_b32_e32 v13, 11, v153
	v_lshlrev_b32_e32 v14, 11, v154
	v_lshlrev_b32_e32 v15, 11, v155
	v_lshlrev_b32_e32 v16, 11, v157
	v_lshlrev_b32_e32 v17, 11, v158
	v_lshlrev_b32_e32 v18, 11, v159
	v_lshlrev_b32_e32 v19, 11, v160
	v_lshlrev_b32_e32 v20, 11, v162
	v_lshlrev_b32_e32 v21, 11, v163
	v_lshlrev_b32_e32 v22, 11, v164
	v_lshlrev_b32_e32 v11, 11, v165
	v_lshlrev_b32_sdwa v2, v3, v2 dst_sel:DWORD dst_unused:UNUSED_PAD src0_sel:DWORD src1_sel:BYTE_0
	v_mov_b32_e32 v3, v1
	v_readlane_b32 s1, v252, 29
	v_lshl_add_u64 v[58:59], v[56:57], 0, s[66:67]
	v_lshl_add_u64 v[64:65], v[56:57], 0, s[8:9]
	v_mul_u32_u24_e32 v147, 0x210, v144
	v_mul_u32_u24_e32 v151, 0x210, v150
	v_mul_u32_u24_e32 v156, 0x210, v155
	v_mul_u32_u24_e32 v161, 0x210, v160
	v_mul_u32_u24_e32 v166, 0x210, v165
	v_lshl_add_u64 v[68:69], v[56:57], 0, s[62:63]
	v_add_u32_e32 v167, 64, v146
	v_lshl_add_u64 v[86:87], s[0:1], 0, v[2:3]
	v_add_u32_e32 v168, v143, v8
	v_add_u32_e32 v0, v10, v0
	v_add_u32_e32 v169, v6, v4
	v_add_u32_e32 v170, v6, v5
	v_add_u32_e32 v171, v6, v7
	v_add_u32_e32 v172, v6, v9
	v_add_u32_e32 v173, v6, v12
	v_add_u32_e32 v174, v6, v13
	v_add_u32_e32 v175, v6, v14
	v_add_u32_e32 v176, v6, v15
	v_add_u32_e32 v177, v6, v16
	v_add_u32_e32 v178, v6, v17
	v_add_u32_e32 v179, v6, v18
	v_add_u32_e32 v180, v6, v19
	v_add_u32_e32 v181, v6, v20
	v_add_u32_e32 v182, v6, v21
	v_add_u32_e32 v183, v6, v22
	v_add_u32_e32 v184, v6, v11
	global_load_dwordx4 v[186:189], v[56:57], off
	global_load_dwordx4 v[190:193], v[56:57], off offset:32
	global_load_dwordx4 v[194:197], v[58:59], off
	global_load_dwordx4 v[202:205], v[60:61], off
	global_load_dwordx4 v[206:209], v[56:57], off offset:64
	global_load_dwordx4 v[226:229], v[62:63], off
	global_load_dwordx4 v[230:233], v[56:57], off offset:96
	global_load_dwordx4 v[234:237], v[64:65], off
	global_load_dwordx4 v[238:241], v[68:69], off
	global_load_dwordx4 v[242:245], v[70:71], off
	global_load_dwordx4 v[246:249], v[72:73], off
	global_load_dwordx4 v[60:63], v[82:83], off
	s_mov_b32 s10, s79
	s_branch .LBB0_552

; #define LAS __attribute__((address_space(3)))
; __device__ __forceinline__ unsigned pk2(float lo, float hi) { return f2bf(lo) | (f2bf(hi) << 16); }
; __device__ __forceinline__ float fsig(float x) { return __builtin_amdgcn_rcpf(1.0f + __expf(-x)); }
; __device__ __forceinline__ int crow16(int r, int hi) { return (r & 3) + 8 * (r >> 2) + 4 * hi; }
; __device__ __forceinline__ void lru_pass1_unit(int cu4, const Args& a, int l, const bf16* LX, const bf16* WLRU, h2* AD, float2* LCS4, lds_t* lds, int tid, int lane, int wave, const LruGateC& gc) {
;     ...
;             v4u ow;
; #pragma unroll
;             for (int e = 0; e < 4; ++e) ow[e] = pk2(acc[2 * e], acc[2 * e + 1]);
;             *(LAS v4u*)(XR + (t & 31) * LR_LDX + w8 * 2) = ow; } }
;     __syncthreads();
;     const int k = wave & 3, dir = wave >> 2;
;     const float (&ba)[2] = gc.ba; const float (&bx)[2] = gc.bx; const float (&lsl)[2] = gc.lsl;
;     float At = 1.f, Ht = 0.f;
;     for (int rt = rt0; rt < rt0 + 1; ++rt) {
;         bf16x8 af[4];
; #pragma unroll
;         for (int ks = 0; ks < 4; ++ks) af[ks] = *(const LAS bf16x8*)(XR + (lane & 31) * LR_LDX + (64 * k + 16 * ks + 8 * (lane >> 5)) * 2);
; #pragma unroll
;         for (int ct = 0; ct < 2; ++ct) { f32x16 ga = {}, gx = {};
; #pragma unroll
;             for (int ks = 0; ks < 4; ++ks) { const bf16* wb = WLRU + (((size_t)(l * 2 + dir) * 2 * 4 + k) * 64 + 32 * ct + (lane & 31)) * 64 + 16 * ks + 8 * (lane >> 5);
;                 ga = __builtin_amdgcn_mfma_f32_32x32x16_bf16(af[ks], *(const bf16x8*)wb, ga, 0, 0, 0); gx = __builtin_amdgcn_mfma_f32_32x32x16_bf16(af[ks], *(const bf16x8*)(wb + 4 * 4096), gx, 0, 0, 0); }
;             const int ch = 64 * k + 32 * ct + (lane & 31);
; #pragma unroll
;             for (int r = 0; r < 16; ++r) { const int row = crow16(r, lane >> 5);
;                 const float rg = fsig(ga[r] + ba[ct]), ig = fsig(gx[r] + bx[ct]); const float la = lsl[ct] * rg;
;                 const float a_ = __expf(la); const float oma = 1.0f - a_, dr = __builtin_amdgcn_sqrtf(oma * (1.0f + a_)) * ig * bf2f(*(const LAS unsigned short*)(XR + row * LR_LDX + ch * 2));
;                 h2 hv; hv[0] = (_Float16)oma; hv[1] = (_Float16)dr;
;                 ADL[row * 512 + dir * 256 + ch] = hv; AD[((size_t)(m0 + 32 * rt + row) * 2 + dir) * 256 + ch] = hv; } }
.LBB0_572:
	s_or_b64 exec, exec, s[0:1]
	v_bfe_u32 v10, v6, 16, 1
	v_add3_u32 v6, v6, v10, s33
	v_bfe_u32 v10, v7, 16, 1
	v_lshrrev_b32_e32 v6, 16, v6
	v_add3_u32 v7, v7, v10, s33
	v_and_or_b32 v6, v7, s87, v6
	v_bfe_u32 v7, v8, 16, 1
	v_add3_u32 v7, v8, v7, s33
	v_bfe_u32 v8, v9, 16, 1
	v_lshrrev_b32_e32 v7, 16, v7
	v_add3_u32 v8, v9, v8, s33
	v_and_or_b32 v7, v8, s87, v7
	v_bfe_u32 v8, v2, 16, 1
	v_add3_u32 v2, v2, v8, s33
	v_bfe_u32 v8, v3, 16, 1
	v_lshrrev_b32_e32 v2, 16, v2
	v_add3_u32 v3, v3, v8, s33
	v_and_or_b32 v8, v3, s87, v2
	v_bfe_u32 v2, v4, 16, 1
	v_add3_u32 v2, v4, v2, s33
	v_bfe_u32 v3, v5, 16, 1
	v_lshrrev_b32_e32 v2, 16, v2
	v_add3_u32 v3, v5, v3, s33
	v_and_or_b32 v9, v3, s87, v2
	v_and_b32_e32 v2, 31, v44
	v_mad_u32_u24 v2, v2, s51, v143
	ds_write_b128 v2, v[6:9]
	global_load_dwordx4 v[114:117], v[74:75], off
	global_load_dwordx4 v[118:121], v[76:77], off
	global_load_dwordx4 v[122:125], v[78:79], off
	global_load_dwordx4 v[126:129], v[80:81], off
	s_waitcnt lgkmcnt(0)
	s_barrier
	ds_read_b128 v[46:49], v0
	ds_read_b128 v[42:45], v0 offset:32
	s_waitcnt vmcnt(0)
	ds_read_b128 v[38:41], v0 offset:64
	ds_read_b128 v[34:37], v0 offset:96
	s_add_i32 s0, s12, s13
	s_waitcnt vmcnt(1) lgkmcnt(3)
	v_mfma_f32_32x32x16_bf16 v[18:33], v[46:49], v[186:189], 0
	s_waitcnt vmcnt(1) lgkmcnt(2)
	v_mfma_f32_32x32x16_bf16 v[18:33], v[42:45], v[190:193], v[18:33]
	s_waitcnt vmcnt(1)
	v_mfma_f32_32x32x16_bf16 v[2:17], v[46:49], v[194:197], 0
	s_waitcnt vmcnt(0)
	v_mfma_f32_32x32x16_bf16 v[2:17], v[42:45], v[202:205], v[2:17]
	s_waitcnt vmcnt(0) lgkmcnt(1)
	v_mfma_f32_32x32x16_bf16 v[18:33], v[38:41], v[206:209], v[18:33]
	s_waitcnt vmcnt(0)
	v_mfma_f32_32x32x16_bf16 v[2:17], v[38:41], v[226:229], v[2:17]
	s_waitcnt vmcnt(0) lgkmcnt(0)
	v_mfma_f32_32x32x16_bf16 v[18:33], v[34:37], v[230:233], v[18:33]
	s_nop 10
	v_add_f32_e32 v18, v136, v18
	v_mul_f32_e32 v18, 0xbfb8aa3b, v18
	v_exp_f32_e32 v18, v18
	s_waitcnt vmcnt(0)
	v_mfma_f32_32x32x16_bf16 v[2:17], v[34:37], v[234:237], v[2:17]
	v_add_f32_e32 v18, 1.0, v18
	v_rcp_f32_e32 v18, v18
	s_nop 9
	v_add_f32_e32 v2, v138, v2
	v_mul_f32_e32 v18, v140, v18
	v_mul_f32_e32 v18, 0x3fb8aa3b, v18
	v_mul_f32_e32 v2, 0xbfb8aa3b, v2
	v_exp_f32_e32 v18, v18
	v_exp_f32_e32 v2, v2
	v_add_f32_e32 v3, v138, v3
	v_mul_f32_e32 v3, 0xbfb8aa3b, v3
	v_sub_f32_e32 v88, 1.0, v18
	v_add_f32_e32 v18, 1.0, v18
	v_add_f32_e32 v2, 1.0, v2
	v_mul_f32_e32 v18, v88, v18
	v_rcp_f32_e32 v2, v2
	v_sqrt_f32_e32 v18, v18
	v_exp_f32_e32 v3, v3
	v_add_f32_e32 v4, v138, v4
	v_mul_f32_e32 v4, 0xbfb8aa3b, v4
	v_mul_f32_e32 v18, v2, v18
	v_add_u32_e32 v2, v146, v147
	ds_read_u16 v89, v2
	ds_read_u16 v56, v2 offset:528
	ds_read_u16 v57, v2 offset:1056
	v_add_u32_e32 v58, v146, v151
	ds_read_u16 v58, v58
	ds_read_u16 v59, v2 offset:4224
	ds_read_u16 v64, v2 offset:4752
	ds_read_u16 v65, v2 offset:5280
	v_add_u32_e32 v68, v146, v156
	ds_read_u16 v68, v68
	ds_read_u16 v69, v2 offset:8448
	ds_read_u16 v70, v2 offset:8976
	ds_read_u16 v71, v2 offset:9504
	v_add_u32_e32 v72, v146, v161
	ds_read_u16 v72, v72
	ds_read_u16 v73, v2 offset:12672
	ds_read_u16 v210, v2 offset:13200
	ds_read_u16 v211, v2 offset:13728
	v_add_u32_e32 v214, v146, v166
	ds_read_u16 v214, v214
	v_add_f32_e32 v3, 1.0, v3
	v_rcp_f32_e32 v3, v3
	v_exp_f32_e32 v4, v4
	s_waitcnt lgkmcnt(0)
	v_lshlrev_b32_e32 v89, 16, v89
	v_mul_f32_e32 v18, v18, v89
	v_cvt_pk_f16_f32 v18, v88, v18
	v_add_u32_e32 v88, s0, v144
	v_ashrrev_i32_e32 v89, 31, v88
	v_lshlrev_b64 v[88:89], 11, v[88:89]
	v_lshl_add_u64 v[92:93], v[66:67], 0, v[88:89]
	ds_write_b32 v169, v18
	global_store_dword v[92:93], v18, off
	v_add_f32_e32 v18, v136, v19
	v_mul_f32_e32 v18, 0xbfb8aa3b, v18
	v_exp_f32_e32 v18, v18
	v_add_f32_e32 v4, 1.0, v4
	v_rcp_f32_e32 v4, v4
	v_add_f32_e32 v18, 1.0, v18
	v_rcp_f32_e32 v18, v18
	s_nop 0
	v_mul_f32_e32 v18, v140, v18
	v_mul_f32_e32 v18, 0x3fb8aa3b, v18
	v_exp_f32_e32 v18, v18
	s_nop 0
	v_sub_f32_e32 v19, 1.0, v18
	v_add_f32_e32 v18, 1.0, v18
	v_mul_f32_e32 v18, v19, v18
	v_sqrt_f32_e32 v18, v18
	s_nop 0
	v_mul_f32_e32 v3, v3, v18
	v_lshlrev_b32_e32 v18, 16, v56
	v_mul_f32_e32 v3, v3, v18
	v_add_u32_e32 v18, s0, v148
	v_cvt_pk_f16_f32 v3, v19, v3
	v_ashrrev_i32_e32 v19, 31, v18
	v_lshlrev_b64 v[18:19], 11, v[18:19]
	v_lshl_add_u64 v[90:91], v[66:67], 0, v[18:19]
	ds_write_b32 v170, v3
	global_store_dword v[90:91], v3, off
	v_add_f32_e32 v3, v136, v20
	v_mul_f32_e32 v3, 0xbfb8aa3b, v3
	v_exp_f32_e32 v3, v3
	s_nop 0
	v_add_f32_e32 v3, 1.0, v3
	v_rcp_f32_e32 v3, v3
	s_nop 0
	v_mul_f32_e32 v3, v140, v3
	v_mul_f32_e32 v3, 0x3fb8aa3b, v3
	v_exp_f32_e32 v3, v3
	s_nop 0
	v_sub_f32_e32 v18, 1.0, v3
	v_add_f32_e32 v3, 1.0, v3
	v_mul_f32_e32 v3, v18, v3
	v_sqrt_f32_e32 v3, v3
	s_nop 0
	v_mul_f32_e32 v3, v4, v3
	v_lshlrev_b32_e32 v4, 16, v57
	v_mul_f32_e32 v3, v3, v4
	v_cvt_pk_f16_f32 v3, v18, v3
	v_add_u32_e32 v18, s0, v149
	v_ashrrev_i32_e32 v19, 31, v18
	v_lshlrev_b64 v[18:19], 11, v[18:19]
	v_lshl_add_u64 v[88:89], v[66:67], 0, v[18:19]
	ds_write_b32 v171, v3
	global_store_dword v[88:89], v3, off
	v_add_f32_e32 v3, v136, v21
	v_mul_f32_e32 v3, 0xbfb8aa3b, v3
	v_exp_f32_e32 v3, v3
	v_add_f32_e32 v4, v138, v5
	v_mul_f32_e32 v4, 0xbfb8aa3b, v4
	v_exp_f32_e32 v4, v4
	v_add_f32_e32 v3, 1.0, v3
	v_rcp_f32_e32 v3, v3
	v_add_f32_e32 v4, 1.0, v4
	v_rcp_f32_e32 v4, v4
	v_mul_f32_e32 v3, v140, v3
	v_mul_f32_e32 v3, 0x3fb8aa3b, v3
	v_exp_f32_e32 v3, v3
	s_nop 0
	v_sub_f32_e32 v5, 1.0, v3
	v_add_f32_e32 v3, 1.0, v3
	v_mul_f32_e32 v3, v5, v3
	v_sqrt_f32_e32 v3, v3
	s_nop 0
	v_mul_f32_e32 v3, v4, v3
	v_lshlrev_b32_e32 v4, 16, v58
	v_mul_f32_e32 v3, v3, v4
	v_add_u32_e32 v4, s0, v150
	v_cvt_pk_f16_f32 v3, v5, v3
; #define LAS __attribute__((address_space(3)))
; __device__ __forceinline__ float fsig(float x) { return __builtin_amdgcn_rcpf(1.0f + __expf(-x)); }
; __device__ __forceinline__ int crow16(int r, int hi) { return (r & 3) + 8 * (r >> 2) + 4 * hi; }
; __device__ __forceinline__ void lru_pass1_unit(int cu4, const Args& a, int l, const bf16* LX, const bf16* WLRU, h2* AD, float2* LCS4, lds_t* lds, int tid, int lane, int wave, const LruGateC& gc) {
;     ...
;             for (int r = 0; r < 16; ++r) { const int row = crow16(r, lane >> 5);
;                 const float rg = fsig(ga[r] + ba[ct]), ig = fsig(gx[r] + bx[ct]); const float la = lsl[ct] * rg;
;                 const float a_ = __expf(la); const float oma = 1.0f - a_, dr = __builtin_amdgcn_sqrtf(oma * (1.0f + a_)) * ig * bf2f(*(const LAS unsigned short*)(XR + row * LR_LDX + ch * 2));
;                 h2 hv; hv[0] = (_Float16)oma; hv[1] = (_Float16)dr;
;                 ADL[row * 512 + dir * 256 + ch] = hv; AD[((size_t)(m0 + 32 * rt + row) * 2 + dir) * 256 + ch] = hv; } }
	v_ashrrev_i32_e32 v5, 31, v4
	v_lshlrev_b64 v[4:5], 11, v[4:5]
	v_lshl_add_u64 v[94:95], v[66:67], 0, v[4:5]
	ds_write_b32 v172, v3
	global_store_dword v[94:95], v3, off
	v_add_f32_e32 v3, v136, v22
	v_mul_f32_e32 v3, 0xbfb8aa3b, v3
	v_exp_f32_e32 v3, v3
	v_add_f32_e32 v4, v138, v6
	v_mul_f32_e32 v4, 0xbfb8aa3b, v4
	v_exp_f32_e32 v4, v4
	v_add_f32_e32 v3, 1.0, v3
	v_rcp_f32_e32 v3, v3
	v_add_f32_e32 v4, 1.0, v4
	v_rcp_f32_e32 v4, v4
	v_mul_f32_e32 v3, v140, v3
	v_mul_f32_e32 v3, 0x3fb8aa3b, v3
	v_exp_f32_e32 v3, v3
	s_nop 0
	v_sub_f32_e32 v5, 1.0, v3
	v_add_f32_e32 v3, 1.0, v3
	v_mul_f32_e32 v3, v5, v3
	v_sqrt_f32_e32 v3, v3
	s_nop 0
	v_mul_f32_e32 v3, v4, v3
	v_lshlrev_b32_e32 v4, 16, v59
	v_mul_f32_e32 v3, v3, v4
	v_add_u32_e32 v4, s0, v152
	v_cvt_pk_f16_f32 v3, v5, v3
	v_ashrrev_i32_e32 v5, 31, v4
	v_lshlrev_b64 v[4:5], 11, v[4:5]
	v_lshl_add_u64 v[96:97], v[66:67], 0, v[4:5]
	ds_write_b32 v173, v3
	global_store_dword v[96:97], v3, off
	v_add_f32_e32 v3, v136, v23
	v_mul_f32_e32 v3, 0xbfb8aa3b, v3
	v_exp_f32_e32 v3, v3
	v_add_f32_e32 v4, v138, v7
	v_mul_f32_e32 v4, 0xbfb8aa3b, v4
	v_exp_f32_e32 v4, v4
	v_add_f32_e32 v3, 1.0, v3
	v_rcp_f32_e32 v3, v3
	v_add_f32_e32 v4, 1.0, v4
	v_rcp_f32_e32 v4, v4
	v_mul_f32_e32 v3, v140, v3
	v_mul_f32_e32 v3, 0x3fb8aa3b, v3
	v_exp_f32_e32 v3, v3
	s_nop 0
	v_sub_f32_e32 v5, 1.0, v3
	v_add_f32_e32 v3, 1.0, v3
	v_mul_f32_e32 v3, v5, v3
	v_sqrt_f32_e32 v3, v3
	s_nop 0
	v_mul_f32_e32 v3, v4, v3
	v_lshlrev_b32_e32 v4, 16, v64
	v_mul_f32_e32 v3, v3, v4
	v_add_u32_e32 v4, s0, v153
	v_cvt_pk_f16_f32 v3, v5, v3
	v_ashrrev_i32_e32 v5, 31, v4
	v_lshlrev_b64 v[4:5], 11, v[4:5]
	v_lshl_add_u64 v[98:99], v[66:67], 0, v[4:5]
	ds_write_b32 v174, v3
	global_store_dword v[98:99], v3, off
	v_add_f32_e32 v3, v136, v24
	v_mul_f32_e32 v3, 0xbfb8aa3b, v3
	v_exp_f32_e32 v3, v3
	v_add_f32_e32 v4, v138, v8
	v_mul_f32_e32 v4, 0xbfb8aa3b, v4
	v_exp_f32_e32 v4, v4
	v_add_f32_e32 v3, 1.0, v3
	v_rcp_f32_e32 v3, v3
	v_add_f32_e32 v4, 1.0, v4
	v_rcp_f32_e32 v4, v4
	v_mul_f32_e32 v3, v140, v3
	v_mul_f32_e32 v3, 0x3fb8aa3b, v3
	v_exp_f32_e32 v3, v3
	s_nop 0
	v_sub_f32_e32 v5, 1.0, v3
	v_add_f32_e32 v3, 1.0, v3
	v_mul_f32_e32 v3, v5, v3
	v_sqrt_f32_e32 v3, v3
	s_nop 0
	v_mul_f32_e32 v3, v4, v3
	v_lshlrev_b32_e32 v4, 16, v65
	v_mul_f32_e32 v3, v3, v4
	v_add_u32_e32 v4, s0, v154
	v_cvt_pk_f16_f32 v3, v5, v3
	v_ashrrev_i32_e32 v5, 31, v4
	v_lshlrev_b64 v[4:5], 11, v[4:5]
	v_lshl_add_u64 v[100:101], v[66:67], 0, v[4:5]
	ds_write_b32 v175, v3
	global_store_dword v[100:101], v3, off
	v_add_f32_e32 v3, v136, v25
	v_mul_f32_e32 v3, 0xbfb8aa3b, v3
	v_exp_f32_e32 v3, v3
	v_add_f32_e32 v4, v138, v9
	v_mul_f32_e32 v4, 0xbfb8aa3b, v4
	v_exp_f32_e32 v4, v4
	v_add_f32_e32 v3, 1.0, v3
	v_rcp_f32_e32 v3, v3
	v_add_f32_e32 v4, 1.0, v4
	v_rcp_f32_e32 v4, v4
	v_mul_f32_e32 v3, v140, v3
	v_mul_f32_e32 v3, 0x3fb8aa3b, v3
	v_exp_f32_e32 v3, v3
	s_nop 0
	v_sub_f32_e32 v5, 1.0, v3
	v_add_f32_e32 v3, 1.0, v3
	v_mul_f32_e32 v3, v5, v3
	v_sqrt_f32_e32 v3, v3
	s_nop 0
	v_mul_f32_e32 v3, v4, v3
	v_lshlrev_b32_e32 v4, 16, v68
	v_mul_f32_e32 v3, v3, v4
	v_add_u32_e32 v4, s0, v155
	v_cvt_pk_f16_f32 v3, v5, v3
	v_ashrrev_i32_e32 v5, 31, v4
	v_lshlrev_b64 v[4:5], 11, v[4:5]
	v_lshl_add_u64 v[102:103], v[66:67], 0, v[4:5]
	ds_write_b32 v176, v3
	global_store_dword v[102:103], v3, off
	v_add_f32_e32 v3, v136, v26
	v_mul_f32_e32 v3, 0xbfb8aa3b, v3
	v_exp_f32_e32 v3, v3
	v_add_f32_e32 v4, v138, v10
	v_mul_f32_e32 v4, 0xbfb8aa3b, v4
	v_exp_f32_e32 v4, v4
	v_add_f32_e32 v3, 1.0, v3
	v_rcp_f32_e32 v3, v3
	v_add_f32_e32 v4, 1.0, v4
	v_rcp_f32_e32 v4, v4
	v_mul_f32_e32 v3, v140, v3
	v_mul_f32_e32 v3, 0x3fb8aa3b, v3
	v_exp_f32_e32 v3, v3
	s_nop 0
	v_sub_f32_e32 v5, 1.0, v3
	v_add_f32_e32 v3, 1.0, v3
	v_mul_f32_e32 v3, v5, v3
	v_sqrt_f32_e32 v3, v3
	s_nop 0
	v_mul_f32_e32 v3, v4, v3
	v_lshlrev_b32_e32 v4, 16, v69
	v_mul_f32_e32 v3, v3, v4
	v_add_u32_e32 v4, s0, v157
	v_cvt_pk_f16_f32 v3, v5, v3
	v_ashrrev_i32_e32 v5, 31, v4
	v_lshlrev_b64 v[4:5], 11, v[4:5]
	v_lshl_add_u64 v[104:105], v[66:67], 0, v[4:5]
	ds_write_b32 v177, v3
	global_store_dword v[104:105], v3, off
	v_add_f32_e32 v3, v136, v27
	v_mul_f32_e32 v3, 0xbfb8aa3b, v3
	v_exp_f32_e32 v3, v3
	v_add_f32_e32 v4, v138, v11
	v_mul_f32_e32 v4, 0xbfb8aa3b, v4
	v_exp_f32_e32 v4, v4
	v_add_f32_e32 v3, 1.0, v3
	v_rcp_f32_e32 v3, v3
	v_add_f32_e32 v4, 1.0, v4
	v_rcp_f32_e32 v4, v4
	v_mul_f32_e32 v3, v140, v3
	v_mul_f32_e32 v3, 0x3fb8aa3b, v3
	v_exp_f32_e32 v3, v3
	s_nop 0
	v_sub_f32_e32 v5, 1.0, v3
	v_add_f32_e32 v3, 1.0, v3
	v_mul_f32_e32 v3, v5, v3
	v_sqrt_f32_e32 v3, v3
	s_nop 0
	v_mul_f32_e32 v3, v4, v3
	v_lshlrev_b32_e32 v4, 16, v70
	v_mul_f32_e32 v3, v3, v4
	v_add_u32_e32 v4, s0, v158
	v_cvt_pk_f16_f32 v3, v5, v3
	v_ashrrev_i32_e32 v5, 31, v4
	v_lshlrev_b64 v[4:5], 11, v[4:5]
	v_lshl_add_u64 v[106:107], v[66:67], 0, v[4:5]
	ds_write_b32 v178, v3
	global_store_dword v[106:107], v3, off
	v_add_f32_e32 v3, v136, v28
	v_mul_f32_e32 v3, 0xbfb8aa3b, v3
	v_exp_f32_e32 v3, v3
	v_add_f32_e32 v4, v138, v12
	v_mul_f32_e32 v4, 0xbfb8aa3b, v4
	v_exp_f32_e32 v4, v4
	v_add_f32_e32 v3, 1.0, v3
	v_rcp_f32_e32 v3, v3
	v_add_f32_e32 v4, 1.0, v4
	v_rcp_f32_e32 v4, v4
	v_mul_f32_e32 v3, v140, v3
	v_mul_f32_e32 v3, 0x3fb8aa3b, v3
	v_exp_f32_e32 v3, v3
	s_nop 0
	v_sub_f32_e32 v5, 1.0, v3
	v_add_f32_e32 v3, 1.0, v3
	v_mul_f32_e32 v3, v5, v3
	v_sqrt_f32_e32 v3, v3
	s_nop 0
	v_mul_f32_e32 v3, v4, v3
	v_lshlrev_b32_e32 v4, 16, v71
	v_mul_f32_e32 v3, v3, v4
	v_add_u32_e32 v4, s0, v159
	v_cvt_pk_f16_f32 v3, v5, v3
	v_ashrrev_i32_e32 v5, 31, v4
	v_lshlrev_b64 v[4:5], 11, v[4:5]
	v_lshl_add_u64 v[108:109], v[66:67], 0, v[4:5]
	ds_write_b32 v179, v3
; #define LAS __attribute__((address_space(3)))
; __device__ __forceinline__ float fsig(float x) { return __builtin_amdgcn_rcpf(1.0f + __expf(-x)); }
; __device__ __forceinline__ int crow16(int r, int hi) { return (r & 3) + 8 * (r >> 2) + 4 * hi; }
; __device__ __forceinline__ void lru_pass1_unit(int cu4, const Args& a, int l, const bf16* LX, const bf16* WLRU, h2* AD, float2* LCS4, lds_t* lds, int tid, int lane, int wave, const LruGateC& gc) {
;     ...
;         for (int ks = 0; ks < 4; ++ks) af[ks] = *(const LAS bf16x8*)(XR + (lane & 31) * LR_LDX + (64 * k + 16 * ks + 8 * (lane >> 5)) * 2);
; #pragma unroll
;         for (int ct = 0; ct < 2; ++ct) { f32x16 ga = {}, gx = {};
; #pragma unroll
;             for (int ks = 0; ks < 4; ++ks) { const bf16* wb = WLRU + (((size_t)(l * 2 + dir) * 2 * 4 + k) * 64 + 32 * ct + (lane & 31)) * 64 + 16 * ks + 8 * (lane >> 5);
;                 ga = __builtin_amdgcn_mfma_f32_32x32x16_bf16(af[ks], *(const bf16x8*)wb, ga, 0, 0, 0); gx = __builtin_amdgcn_mfma_f32_32x32x16_bf16(af[ks], *(const bf16x8*)(wb + 4 * 4096), gx, 0, 0, 0); }
;             const int ch = 64 * k + 32 * ct + (lane & 31);
; #pragma unroll
;             for (int r = 0; r < 16; ++r) { const int row = crow16(r, lane >> 5);
;                 const float rg = fsig(ga[r] + ba[ct]), ig = fsig(gx[r] + bx[ct]); const float la = lsl[ct] * rg;
;                 const float a_ = __expf(la); const float oma = 1.0f - a_, dr = __builtin_amdgcn_sqrtf(oma * (1.0f + a_)) * ig * bf2f(*(const LAS unsigned short*)(XR + row * LR_LDX + ch * 2));
;                 h2 hv; hv[0] = (_Float16)oma; hv[1] = (_Float16)dr;
;                 ADL[row * 512 + dir * 256 + ch] = hv; AD[((size_t)(m0 + 32 * rt + row) * 2 + dir) * 256 + ch] = hv; } }
	global_store_dword v[108:109], v3, off
	v_add_f32_e32 v3, v136, v29
	v_mul_f32_e32 v3, 0xbfb8aa3b, v3
	v_exp_f32_e32 v3, v3
	v_add_f32_e32 v4, v138, v13
	v_mul_f32_e32 v4, 0xbfb8aa3b, v4
	v_exp_f32_e32 v4, v4
	v_add_f32_e32 v3, 1.0, v3
	v_rcp_f32_e32 v3, v3
	v_add_f32_e32 v4, 1.0, v4
	v_rcp_f32_e32 v4, v4
	v_mul_f32_e32 v3, v140, v3
	v_mul_f32_e32 v3, 0x3fb8aa3b, v3
	v_exp_f32_e32 v3, v3
	s_nop 0
	v_sub_f32_e32 v5, 1.0, v3
	v_add_f32_e32 v3, 1.0, v3
	v_mul_f32_e32 v3, v5, v3
	v_sqrt_f32_e32 v3, v3
	s_nop 0
	v_mul_f32_e32 v3, v4, v3
	v_lshlrev_b32_e32 v4, 16, v72
	v_mul_f32_e32 v3, v3, v4
	v_add_u32_e32 v4, s0, v160
	v_cvt_pk_f16_f32 v3, v5, v3
	v_ashrrev_i32_e32 v5, 31, v4
	v_lshlrev_b64 v[4:5], 11, v[4:5]
	v_lshl_add_u64 v[110:111], v[66:67], 0, v[4:5]
	ds_write_b32 v180, v3
	global_store_dword v[110:111], v3, off
	v_add_f32_e32 v3, v136, v30
	v_mul_f32_e32 v3, 0xbfb8aa3b, v3
	v_exp_f32_e32 v3, v3
	v_add_f32_e32 v4, v138, v14
	v_mul_f32_e32 v4, 0xbfb8aa3b, v4
	v_exp_f32_e32 v4, v4
	v_add_f32_e32 v3, 1.0, v3
	v_rcp_f32_e32 v3, v3
	v_add_f32_e32 v4, 1.0, v4
	v_rcp_f32_e32 v4, v4
	v_mul_f32_e32 v3, v140, v3
	v_mul_f32_e32 v3, 0x3fb8aa3b, v3
	v_exp_f32_e32 v3, v3
	s_nop 0
	v_sub_f32_e32 v5, 1.0, v3
	v_add_f32_e32 v3, 1.0, v3
	v_mul_f32_e32 v3, v5, v3
	v_sqrt_f32_e32 v3, v3
	s_nop 0
	v_mul_f32_e32 v3, v4, v3
	v_lshlrev_b32_e32 v4, 16, v73
	v_mul_f32_e32 v3, v3, v4
	v_add_u32_e32 v4, s0, v162
	v_cvt_pk_f16_f32 v3, v5, v3
	v_ashrrev_i32_e32 v5, 31, v4
	v_lshlrev_b64 v[4:5], 11, v[4:5]
	v_lshl_add_u64 v[112:113], v[66:67], 0, v[4:5]
	ds_write_b32 v181, v3
	global_store_dword v[112:113], v3, off
	v_add_f32_e32 v3, v136, v31
	v_mul_f32_e32 v3, 0xbfb8aa3b, v3
	v_exp_f32_e32 v3, v3
	v_add_f32_e32 v4, v138, v15
	v_mul_f32_e32 v4, 0xbfb8aa3b, v4
	v_exp_f32_e32 v4, v4
	v_add_f32_e32 v3, 1.0, v3
	v_rcp_f32_e32 v3, v3
	v_add_f32_e32 v4, 1.0, v4
	v_rcp_f32_e32 v4, v4
	v_mul_f32_e32 v3, v140, v3
	v_mul_f32_e32 v3, 0x3fb8aa3b, v3
	v_exp_f32_e32 v3, v3
	s_nop 0
	v_sub_f32_e32 v5, 1.0, v3
	v_add_f32_e32 v3, 1.0, v3
	v_mul_f32_e32 v3, v5, v3
	v_sqrt_f32_e32 v3, v3
	s_nop 0
	v_mul_f32_e32 v3, v4, v3
	v_lshlrev_b32_e32 v4, 16, v210
	v_mul_f32_e32 v3, v3, v4
	v_add_u32_e32 v4, s0, v163
	v_cvt_pk_f16_f32 v3, v5, v3
	v_ashrrev_i32_e32 v5, 31, v4
	v_lshlrev_b64 v[4:5], 11, v[4:5]
	v_lshl_add_u64 v[130:131], v[66:67], 0, v[4:5]
	ds_write_b32 v182, v3
	global_store_dword v[130:131], v3, off
	v_add_f32_e32 v3, v136, v32
	v_mul_f32_e32 v3, 0xbfb8aa3b, v3
	v_exp_f32_e32 v3, v3
	v_add_f32_e32 v4, v138, v16
	v_mul_f32_e32 v4, 0xbfb8aa3b, v4
	v_exp_f32_e32 v4, v4
	v_add_f32_e32 v3, 1.0, v3
	v_rcp_f32_e32 v3, v3
	v_add_f32_e32 v4, 1.0, v4
	v_rcp_f32_e32 v4, v4
	v_mul_f32_e32 v3, v140, v3
	v_mul_f32_e32 v3, 0x3fb8aa3b, v3
	v_exp_f32_e32 v3, v3
	v_lshlrev_b32_e32 v2, 16, v211
	v_sub_f32_e32 v5, 1.0, v3
	v_add_f32_e32 v3, 1.0, v3
	v_mul_f32_e32 v3, v5, v3
	v_sqrt_f32_e32 v3, v3
	s_nop 0
	v_mul_f32_e32 v3, v4, v3
	v_mul_f32_e32 v2, v3, v2
	v_cvt_pk_f16_f32 v4, v5, v2
	v_add_u32_e32 v2, s0, v164
	v_ashrrev_i32_e32 v3, 31, v2
	v_lshlrev_b64 v[2:3], 11, v[2:3]
	v_lshl_add_u64 v[132:133], v[66:67], 0, v[2:3]
	v_add_f32_e32 v2, v136, v33
	v_mul_f32_e32 v2, 0xbfb8aa3b, v2
	v_exp_f32_e32 v2, v2
	v_add_f32_e32 v3, v138, v17
	v_mul_f32_e32 v3, 0xbfb8aa3b, v3
	v_exp_f32_e32 v3, v3
	v_add_f32_e32 v2, 1.0, v2
	v_rcp_f32_e32 v2, v2
	ds_write_b32 v183, v4
	global_store_dword v[132:133], v4, off
	v_add_f32_e32 v3, 1.0, v3
	v_mul_f32_e32 v2, v140, v2
	v_mul_f32_e32 v2, 0x3fb8aa3b, v2
	v_exp_f32_e32 v2, v2
	v_rcp_f32_e32 v3, v3
	v_sub_f32_e32 v4, 1.0, v2
	v_add_f32_e32 v2, 1.0, v2
	v_mul_f32_e32 v2, v4, v2
	v_sqrt_f32_e32 v2, v2
	s_nop 0
	v_mul_f32_e32 v2, v3, v2
	v_lshlrev_b32_e32 v3, 16, v214
	v_mul_f32_e32 v2, v2, v3
	v_cvt_pk_f16_f32 v4, v4, v2
	v_add_u32_e32 v2, s0, v165
	v_ashrrev_i32_e32 v3, 31, v2
	v_lshlrev_b64 v[2:3], 11, v[2:3]
	v_lshl_add_u64 v[134:135], v[66:67], 0, v[2:3]
	global_store_dword v[134:135], v4, off
	ds_write_b32 v184, v4
	v_mfma_f32_32x32x16_bf16 v[18:33], v[46:49], v[238:241], 0
	v_mfma_f32_32x32x16_bf16 v[2:17], v[46:49], v[242:245], 0
	v_mfma_f32_32x32x16_bf16 v[18:33], v[42:45], v[246:249], v[18:33]
	v_mfma_f32_32x32x16_bf16 v[2:17], v[42:45], v[114:117], v[2:17]
	v_mfma_f32_32x32x16_bf16 v[18:33], v[38:41], v[118:121], v[18:33]
	v_mfma_f32_32x32x16_bf16 v[2:17], v[38:41], v[122:125], v[2:17]
	v_mfma_f32_32x32x16_bf16 v[18:33], v[34:37], v[126:129], v[18:33]
	s_nop 10
	v_add_f32_e32 v18, v137, v18
	v_mul_f32_e32 v18, 0xbfb8aa3b, v18
	v_exp_f32_e32 v18, v18
	v_mfma_f32_32x32x16_bf16 v[2:17], v[34:37], v[60:63], v[2:17]
	v_add_f32_e32 v18, 1.0, v18
	v_rcp_f32_e32 v18, v18
	s_nop 9
	v_add_f32_e32 v2, v139, v2
	v_mul_f32_e32 v18, v141, v18
	v_mul_f32_e32 v18, 0x3fb8aa3b, v18
	v_mul_f32_e32 v2, 0xbfb8aa3b, v2
	v_exp_f32_e32 v18, v18
	v_exp_f32_e32 v2, v2
	v_add_f32_e32 v3, v139, v3
	v_mul_f32_e32 v3, 0xbfb8aa3b, v3
	v_sub_f32_e32 v34, 1.0, v18
	v_add_f32_e32 v18, 1.0, v18
	v_add_f32_e32 v2, 1.0, v2
	v_mul_f32_e32 v18, v34, v18
	v_rcp_f32_e32 v2, v2
	v_sqrt_f32_e32 v18, v18
	v_exp_f32_e32 v3, v3
	v_add_f32_e32 v4, v139, v4
	v_mul_f32_e32 v4, 0xbfb8aa3b, v4
	v_mul_f32_e32 v18, v2, v18
	v_add_u32_e32 v2, v167, v147
	ds_read_u16 v35, v2
	ds_read_u16 v56, v2 offset:528
	ds_read_u16 v57, v2 offset:1056
	v_add_u32_e32 v58, v167, v151
	ds_read_u16 v58, v58
	ds_read_u16 v59, v2 offset:4224
	ds_read_u16 v64, v2 offset:4752
	ds_read_u16 v65, v2 offset:5280
	v_add_u32_e32 v68, v167, v156
	ds_read_u16 v68, v68
	ds_read_u16 v69, v2 offset:8448
	ds_read_u16 v70, v2 offset:8976
	ds_read_u16 v71, v2 offset:9504
	v_add_u32_e32 v72, v167, v161
	ds_read_u16 v72, v72
	ds_read_u16 v73, v2 offset:12672
	ds_read_u16 v210, v2 offset:13200
	ds_read_u16 v211, v2 offset:13728
	v_add_u32_e32 v214, v167, v166
	ds_read_u16 v214, v214
	v_add_f32_e32 v3, 1.0, v3
	v_rcp_f32_e32 v3, v3
	v_exp_f32_e32 v4, v4
	s_waitcnt lgkmcnt(0)
; #define LAS __attribute__((address_space(3)))
; __device__ __forceinline__ float fsig(float x) { return __builtin_amdgcn_rcpf(1.0f + __expf(-x)); }
; __device__ __forceinline__ int crow16(int r, int hi) { return (r & 3) + 8 * (r >> 2) + 4 * hi; }
; __device__ __forceinline__ void lru_pass1_unit(int cu4, const Args& a, int l, const bf16* LX, const bf16* WLRU, h2* AD, float2* LCS4, lds_t* lds, int tid, int lane, int wave, const LruGateC& gc) {
;     ...
;             for (int r = 0; r < 16; ++r) { const int row = crow16(r, lane >> 5);
;                 const float rg = fsig(ga[r] + ba[ct]), ig = fsig(gx[r] + bx[ct]); const float la = lsl[ct] * rg;
;                 const float a_ = __expf(la); const float oma = 1.0f - a_, dr = __builtin_amdgcn_sqrtf(oma * (1.0f + a_)) * ig * bf2f(*(const LAS unsigned short*)(XR + row * LR_LDX + ch * 2));
;                 h2 hv; hv[0] = (_Float16)oma; hv[1] = (_Float16)dr;
;                 ADL[row * 512 + dir * 256 + ch] = hv; AD[((size_t)(m0 + 32 * rt + row) * 2 + dir) * 256 + ch] = hv; } }
	v_lshlrev_b32_e32 v35, 16, v35
	v_mul_f32_e32 v18, v18, v35
	v_cvt_pk_f16_f32 v18, v34, v18
	ds_write_b32 v169, v18 offset:128
	global_store_dword v[92:93], v18, off offset:128
	v_add_f32_e32 v18, v137, v19
	v_mul_f32_e32 v18, 0xbfb8aa3b, v18
	v_exp_f32_e32 v18, v18
	v_add_f32_e32 v4, 1.0, v4
	v_rcp_f32_e32 v4, v4
	v_add_f32_e32 v18, 1.0, v18
	v_rcp_f32_e32 v18, v18
	s_nop 0
	v_mul_f32_e32 v18, v141, v18
	v_mul_f32_e32 v18, 0x3fb8aa3b, v18
	v_exp_f32_e32 v18, v18
	s_nop 0
	v_sub_f32_e32 v19, 1.0, v18
	v_add_f32_e32 v18, 1.0, v18
	v_mul_f32_e32 v18, v19, v18
	v_sqrt_f32_e32 v18, v18
	s_nop 0
	v_mul_f32_e32 v3, v3, v18
	v_lshlrev_b32_e32 v18, 16, v56
	v_mul_f32_e32 v3, v3, v18
	v_cvt_pk_f16_f32 v3, v19, v3
	ds_write_b32 v170, v3 offset:128
	global_store_dword v[90:91], v3, off offset:128
	v_add_f32_e32 v3, v137, v20
	v_mul_f32_e32 v3, 0xbfb8aa3b, v3
	v_exp_f32_e32 v3, v3
	s_nop 0
	v_add_f32_e32 v3, 1.0, v3
	v_rcp_f32_e32 v3, v3
	s_nop 0
	v_mul_f32_e32 v3, v141, v3
	v_mul_f32_e32 v3, 0x3fb8aa3b, v3
	v_exp_f32_e32 v3, v3
	s_nop 0
	v_sub_f32_e32 v18, 1.0, v3
	v_add_f32_e32 v3, 1.0, v3
	v_mul_f32_e32 v3, v18, v3
	v_sqrt_f32_e32 v3, v3
	s_nop 0
	v_mul_f32_e32 v3, v4, v3
	v_lshlrev_b32_e32 v4, 16, v57
	v_mul_f32_e32 v3, v3, v4
	v_cvt_pk_f16_f32 v3, v18, v3
	ds_write_b32 v171, v3 offset:128
	global_store_dword v[88:89], v3, off offset:128
	v_add_f32_e32 v3, v137, v21
	v_mul_f32_e32 v3, 0xbfb8aa3b, v3
	v_exp_f32_e32 v3, v3
	v_add_f32_e32 v4, v139, v5
	v_mul_f32_e32 v4, 0xbfb8aa3b, v4
	v_exp_f32_e32 v4, v4
	v_add_f32_e32 v3, 1.0, v3
	v_rcp_f32_e32 v3, v3
	v_add_f32_e32 v4, 1.0, v4
	v_rcp_f32_e32 v4, v4
	v_mul_f32_e32 v3, v141, v3
	v_mul_f32_e32 v3, 0x3fb8aa3b, v3
	v_exp_f32_e32 v3, v3
	s_nop 0
	v_sub_f32_e32 v5, 1.0, v3
	v_add_f32_e32 v3, 1.0, v3
	v_mul_f32_e32 v3, v5, v3
	v_sqrt_f32_e32 v3, v3
	s_nop 0
	v_mul_f32_e32 v3, v4, v3
	v_lshlrev_b32_e32 v4, 16, v58
	v_mul_f32_e32 v3, v3, v4
	v_cvt_pk_f16_f32 v3, v5, v3
	ds_write_b32 v172, v3 offset:128
	global_store_dword v[94:95], v3, off offset:128
	v_add_f32_e32 v3, v137, v22
	v_mul_f32_e32 v3, 0xbfb8aa3b, v3
	v_exp_f32_e32 v3, v3
	v_add_f32_e32 v4, v139, v6
	v_mul_f32_e32 v4, 0xbfb8aa3b, v4
	v_exp_f32_e32 v4, v4
	v_add_f32_e32 v3, 1.0, v3
	v_rcp_f32_e32 v3, v3
	v_add_f32_e32 v4, 1.0, v4
	v_rcp_f32_e32 v4, v4
	v_mul_f32_e32 v3, v141, v3
	v_mul_f32_e32 v3, 0x3fb8aa3b, v3
	v_exp_f32_e32 v3, v3
	s_nop 0
	v_sub_f32_e32 v5, 1.0, v3
	v_add_f32_e32 v3, 1.0, v3
	v_mul_f32_e32 v3, v5, v3
	v_sqrt_f32_e32 v3, v3
	s_nop 0
	v_mul_f32_e32 v3, v4, v3
	v_lshlrev_b32_e32 v4, 16, v59
	v_mul_f32_e32 v3, v3, v4
	v_cvt_pk_f16_f32 v3, v5, v3
	ds_write_b32 v173, v3 offset:128
	global_store_dword v[96:97], v3, off offset:128
	v_add_f32_e32 v3, v137, v23
	v_mul_f32_e32 v3, 0xbfb8aa3b, v3
	v_exp_f32_e32 v3, v3
	v_add_f32_e32 v4, v139, v7
	v_mul_f32_e32 v4, 0xbfb8aa3b, v4
	v_exp_f32_e32 v4, v4
	v_add_f32_e32 v3, 1.0, v3
	v_rcp_f32_e32 v3, v3
	v_add_f32_e32 v4, 1.0, v4
	v_rcp_f32_e32 v4, v4
	v_mul_f32_e32 v3, v141, v3
	v_mul_f32_e32 v3, 0x3fb8aa3b, v3
	v_exp_f32_e32 v3, v3
	s_nop 0
	v_sub_f32_e32 v5, 1.0, v3
	v_add_f32_e32 v3, 1.0, v3
	v_mul_f32_e32 v3, v5, v3
	v_sqrt_f32_e32 v3, v3
	s_nop 0
	v_mul_f32_e32 v3, v4, v3
	v_lshlrev_b32_e32 v4, 16, v64
	v_mul_f32_e32 v3, v3, v4
	v_cvt_pk_f16_f32 v3, v5, v3
	ds_write_b32 v174, v3 offset:128
	global_store_dword v[98:99], v3, off offset:128
	v_add_f32_e32 v3, v137, v24
	v_mul_f32_e32 v3, 0xbfb8aa3b, v3
	v_exp_f32_e32 v3, v3
	v_add_f32_e32 v4, v139, v8
	v_mul_f32_e32 v4, 0xbfb8aa3b, v4
	v_exp_f32_e32 v4, v4
	v_add_f32_e32 v3, 1.0, v3
	v_rcp_f32_e32 v3, v3
	v_add_f32_e32 v4, 1.0, v4
	v_rcp_f32_e32 v4, v4
	v_mul_f32_e32 v3, v141, v3
	v_mul_f32_e32 v3, 0x3fb8aa3b, v3
	v_exp_f32_e32 v3, v3
	s_nop 0
	v_sub_f32_e32 v5, 1.0, v3
	v_add_f32_e32 v3, 1.0, v3
	v_mul_f32_e32 v3, v5, v3
	v_sqrt_f32_e32 v3, v3
	s_nop 0
	v_mul_f32_e32 v3, v4, v3
	v_lshlrev_b32_e32 v4, 16, v65
	v_mul_f32_e32 v3, v3, v4
	v_cvt_pk_f16_f32 v3, v5, v3
	ds_write_b32 v175, v3 offset:128
	global_store_dword v[100:101], v3, off offset:128
	v_add_f32_e32 v3, v137, v25
	v_mul_f32_e32 v3, 0xbfb8aa3b, v3
	v_exp_f32_e32 v3, v3
	v_add_f32_e32 v4, v139, v9
	v_mul_f32_e32 v4, 0xbfb8aa3b, v4
	v_exp_f32_e32 v4, v4
	v_add_f32_e32 v3, 1.0, v3
	v_rcp_f32_e32 v3, v3
	v_add_f32_e32 v4, 1.0, v4
	v_rcp_f32_e32 v4, v4
	v_mul_f32_e32 v3, v141, v3
	v_mul_f32_e32 v3, 0x3fb8aa3b, v3
	v_exp_f32_e32 v3, v3
	s_nop 0
	v_sub_f32_e32 v5, 1.0, v3
	v_add_f32_e32 v3, 1.0, v3
	v_mul_f32_e32 v3, v5, v3
	v_sqrt_f32_e32 v3, v3
	s_nop 0
	v_mul_f32_e32 v3, v4, v3
	v_lshlrev_b32_e32 v4, 16, v68
	v_mul_f32_e32 v3, v3, v4
	v_cvt_pk_f16_f32 v3, v5, v3
	ds_write_b32 v176, v3 offset:128
	global_store_dword v[102:103], v3, off offset:128
	v_add_f32_e32 v3, v137, v26
	v_mul_f32_e32 v3, 0xbfb8aa3b, v3
	v_exp_f32_e32 v3, v3
	v_add_f32_e32 v4, v139, v10
	v_mul_f32_e32 v4, 0xbfb8aa3b, v4
	v_exp_f32_e32 v4, v4
	v_add_f32_e32 v3, 1.0, v3
	v_rcp_f32_e32 v3, v3
	v_add_f32_e32 v4, 1.0, v4
	v_rcp_f32_e32 v4, v4
	v_mul_f32_e32 v3, v141, v3
	v_mul_f32_e32 v3, 0x3fb8aa3b, v3
	v_exp_f32_e32 v3, v3
	s_nop 0
	v_sub_f32_e32 v5, 1.0, v3
	v_add_f32_e32 v3, 1.0, v3
	v_mul_f32_e32 v3, v5, v3
	v_sqrt_f32_e32 v3, v3
	s_nop 0
	v_mul_f32_e32 v3, v4, v3
	v_lshlrev_b32_e32 v4, 16, v69
	v_mul_f32_e32 v3, v3, v4
	v_cvt_pk_f16_f32 v3, v5, v3
	ds_write_b32 v177, v3 offset:128
	global_store_dword v[104:105], v3, off offset:128
	v_add_f32_e32 v3, v137, v27
	v_mul_f32_e32 v3, 0xbfb8aa3b, v3
	v_exp_f32_e32 v3, v3
	v_add_f32_e32 v4, v139, v11
	v_mul_f32_e32 v4, 0xbfb8aa3b, v4
	v_exp_f32_e32 v4, v4
	v_add_f32_e32 v3, 1.0, v3
	v_rcp_f32_e32 v3, v3
	v_add_f32_e32 v4, 1.0, v4
	v_rcp_f32_e32 v4, v4
; #define LAS __attribute__((address_space(3)))
; __device__ __forceinline__ float fsig(float x) { return __builtin_amdgcn_rcpf(1.0f + __expf(-x)); }
; __device__ __forceinline__ int crow16(int r, int hi) { return (r & 3) + 8 * (r >> 2) + 4 * hi; }
; __device__ __forceinline__ void lru_pass1_unit(int cu4, const Args& a, int l, const bf16* LX, const bf16* WLRU, h2* AD, float2* LCS4, lds_t* lds, int tid, int lane, int wave, const LruGateC& gc) {
;     ...
;             for (int r = 0; r < 16; ++r) { const int row = crow16(r, lane >> 5);
;                 const float rg = fsig(ga[r] + ba[ct]), ig = fsig(gx[r] + bx[ct]); const float la = lsl[ct] * rg;
;                 const float a_ = __expf(la); const float oma = 1.0f - a_, dr = __builtin_amdgcn_sqrtf(oma * (1.0f + a_)) * ig * bf2f(*(const LAS unsigned short*)(XR + row * LR_LDX + ch * 2));
;                 h2 hv; hv[0] = (_Float16)oma; hv[1] = (_Float16)dr;
;                 ADL[row * 512 + dir * 256 + ch] = hv; AD[((size_t)(m0 + 32 * rt + row) * 2 + dir) * 256 + ch] = hv; } }
;         __syncthreads();
	v_mul_f32_e32 v3, v141, v3
	v_mul_f32_e32 v3, 0x3fb8aa3b, v3
	v_exp_f32_e32 v3, v3
	s_nop 0
	v_sub_f32_e32 v5, 1.0, v3
	v_add_f32_e32 v3, 1.0, v3
	v_mul_f32_e32 v3, v5, v3
	v_sqrt_f32_e32 v3, v3
	s_nop 0
	v_mul_f32_e32 v3, v4, v3
	v_lshlrev_b32_e32 v4, 16, v70
	v_mul_f32_e32 v3, v3, v4
	v_cvt_pk_f16_f32 v3, v5, v3
	ds_write_b32 v178, v3 offset:128
	global_store_dword v[106:107], v3, off offset:128
	v_add_f32_e32 v3, v137, v28
	v_mul_f32_e32 v3, 0xbfb8aa3b, v3
	v_exp_f32_e32 v3, v3
	v_add_f32_e32 v4, v139, v12
	v_mul_f32_e32 v4, 0xbfb8aa3b, v4
	v_exp_f32_e32 v4, v4
	v_add_f32_e32 v3, 1.0, v3
	v_rcp_f32_e32 v3, v3
	v_add_f32_e32 v4, 1.0, v4
	v_rcp_f32_e32 v4, v4
	v_mul_f32_e32 v3, v141, v3
	v_mul_f32_e32 v3, 0x3fb8aa3b, v3
	v_exp_f32_e32 v3, v3
	s_nop 0
	v_sub_f32_e32 v5, 1.0, v3
	v_add_f32_e32 v3, 1.0, v3
	v_mul_f32_e32 v3, v5, v3
	v_sqrt_f32_e32 v3, v3
	s_nop 0
	v_mul_f32_e32 v3, v4, v3
	v_lshlrev_b32_e32 v4, 16, v71
	v_mul_f32_e32 v3, v3, v4
	v_cvt_pk_f16_f32 v3, v5, v3
	ds_write_b32 v179, v3 offset:128
	global_store_dword v[108:109], v3, off offset:128
	v_add_f32_e32 v3, v137, v29
	v_mul_f32_e32 v3, 0xbfb8aa3b, v3
	v_exp_f32_e32 v3, v3
	v_add_f32_e32 v4, v139, v13
	v_mul_f32_e32 v4, 0xbfb8aa3b, v4
	v_exp_f32_e32 v4, v4
	v_add_f32_e32 v3, 1.0, v3
	v_rcp_f32_e32 v3, v3
	v_add_f32_e32 v4, 1.0, v4
	v_rcp_f32_e32 v4, v4
	v_mul_f32_e32 v3, v141, v3
	v_mul_f32_e32 v3, 0x3fb8aa3b, v3
	v_exp_f32_e32 v3, v3
	s_nop 0
	v_sub_f32_e32 v5, 1.0, v3
	v_add_f32_e32 v3, 1.0, v3
	v_mul_f32_e32 v3, v5, v3
	v_sqrt_f32_e32 v3, v3
	s_nop 0
	v_mul_f32_e32 v3, v4, v3
	v_lshlrev_b32_e32 v4, 16, v72
	v_mul_f32_e32 v3, v3, v4
	v_cvt_pk_f16_f32 v3, v5, v3
	ds_write_b32 v180, v3 offset:128
	global_store_dword v[110:111], v3, off offset:128
	v_add_f32_e32 v3, v137, v30
	v_mul_f32_e32 v3, 0xbfb8aa3b, v3
	v_exp_f32_e32 v3, v3
	v_add_f32_e32 v4, v139, v14
	v_mul_f32_e32 v4, 0xbfb8aa3b, v4
	v_exp_f32_e32 v4, v4
	v_add_f32_e32 v3, 1.0, v3
	v_rcp_f32_e32 v3, v3
	v_add_f32_e32 v4, 1.0, v4
	v_rcp_f32_e32 v4, v4
	v_mul_f32_e32 v3, v141, v3
	v_mul_f32_e32 v3, 0x3fb8aa3b, v3
	v_exp_f32_e32 v3, v3
	s_nop 0
	v_sub_f32_e32 v5, 1.0, v3
	v_add_f32_e32 v3, 1.0, v3
	v_mul_f32_e32 v3, v5, v3
	v_sqrt_f32_e32 v3, v3
	s_nop 0
	v_mul_f32_e32 v3, v4, v3
	v_lshlrev_b32_e32 v4, 16, v73
	v_mul_f32_e32 v3, v3, v4
	v_cvt_pk_f16_f32 v3, v5, v3
	ds_write_b32 v181, v3 offset:128
	global_store_dword v[112:113], v3, off offset:128
	v_add_f32_e32 v3, v137, v31
	v_mul_f32_e32 v3, 0xbfb8aa3b, v3
	v_exp_f32_e32 v3, v3
	v_add_f32_e32 v4, v139, v15
	v_mul_f32_e32 v4, 0xbfb8aa3b, v4
	v_exp_f32_e32 v4, v4
	v_add_f32_e32 v3, 1.0, v3
	v_rcp_f32_e32 v3, v3
	v_add_f32_e32 v4, 1.0, v4
	v_rcp_f32_e32 v4, v4
	v_mul_f32_e32 v3, v141, v3
	v_mul_f32_e32 v3, 0x3fb8aa3b, v3
	v_exp_f32_e32 v3, v3
	s_nop 0
	v_sub_f32_e32 v5, 1.0, v3
	v_add_f32_e32 v3, 1.0, v3
	v_mul_f32_e32 v3, v5, v3
	v_sqrt_f32_e32 v3, v3
	s_nop 0
	v_mul_f32_e32 v3, v4, v3
	v_lshlrev_b32_e32 v4, 16, v210
	v_mul_f32_e32 v3, v3, v4
	v_cvt_pk_f16_f32 v3, v5, v3
	ds_write_b32 v182, v3 offset:128
	global_store_dword v[130:131], v3, off offset:128
	v_add_f32_e32 v3, v137, v32
	v_mul_f32_e32 v3, 0xbfb8aa3b, v3
	v_exp_f32_e32 v3, v3
	v_add_f32_e32 v4, v139, v16
	v_mul_f32_e32 v4, 0xbfb8aa3b, v4
	v_exp_f32_e32 v4, v4
	v_add_f32_e32 v3, 1.0, v3
	v_rcp_f32_e32 v3, v3
	v_add_f32_e32 v4, 1.0, v4
	v_rcp_f32_e32 v4, v4
	v_mul_f32_e32 v3, v141, v3
	v_mul_f32_e32 v3, 0x3fb8aa3b, v3
	v_exp_f32_e32 v3, v3
	v_lshlrev_b32_e32 v2, 16, v211
	v_sub_f32_e32 v5, 1.0, v3
	v_add_f32_e32 v3, 1.0, v3
	v_mul_f32_e32 v3, v5, v3
	v_sqrt_f32_e32 v3, v3
	s_nop 0
	v_mul_f32_e32 v3, v4, v3
	v_mul_f32_e32 v2, v3, v2
	v_cvt_pk_f16_f32 v2, v5, v2
	ds_write_b32 v183, v2 offset:128
	global_store_dword v[132:133], v2, off offset:128
	v_add_f32_e32 v2, v137, v33
	v_mul_f32_e32 v2, 0xbfb8aa3b, v2
	v_exp_f32_e32 v2, v2
	v_add_f32_e32 v3, v139, v17
	v_mul_f32_e32 v3, 0xbfb8aa3b, v3
	v_exp_f32_e32 v3, v3
	v_add_f32_e32 v2, 1.0, v2
	v_rcp_f32_e32 v2, v2
	v_add_f32_e32 v3, 1.0, v3
	v_rcp_f32_e32 v3, v3
	v_mul_f32_e32 v2, v141, v2
	v_mul_f32_e32 v2, 0x3fb8aa3b, v2
	v_exp_f32_e32 v2, v2
	s_nop 0
	v_sub_f32_e32 v4, 1.0, v2
	v_add_f32_e32 v2, 1.0, v2
	v_mul_f32_e32 v2, v4, v2
	v_sqrt_f32_e32 v2, v2
	s_nop 0
	v_mul_f32_e32 v2, v3, v2
	v_lshlrev_b32_e32 v3, 16, v214
	v_mul_f32_e32 v2, v2, v3
	v_cvt_pk_f16_f32 v2, v4, v2
	ds_write_b32 v184, v2 offset:128
	global_store_dword v[134:135], v2, off offset:128
	s_waitcnt lgkmcnt(0)
	s_barrier
; __device__ __forceinline__ void lru_pass1_unit(int cu4, const Args& a, int l, const bf16* LX, const bf16* WLRU, h2* AD, float2* LCS4, lds_t* lds, int tid, int lane, int wave, const LruGateC& gc) {
;     ...
;         { const int sd = tid >> 8, sc = tid & 255; float A = 1.f, H = 0.f;
;             h2 fr_[32];
; #pragma unroll
;             for (int r = 0; r < 32; ++r) fr_[r] = ADL[r * 512 + sd * 256 + sc];
;             if (sd == 0) {
; #pragma unroll
;                 for (int r = 0; r < 32; ++r) { const float aa = 1.0f - (float)fr_[r][0]; H = aa * H + (float)fr_[r][1]; A *= aa; }
;                 Ht = A * Ht + H; At = A * At; }
;             else {
; #pragma unroll
;                 for (int r = 31; r >= 0; --r) { const float aa = 1.0f - (float)fr_[r][0]; H = aa * H + (float)fr_[r][1]; A *= aa; }
;                 Ht = At * H + Ht; At = At * A; } }
	ds_read2st64_b32 v[2:3], v145 offset1:8
	ds_read2st64_b32 v[4:5], v145 offset0:16 offset1:24
	ds_read2st64_b32 v[6:7], v145 offset0:32 offset1:40
	ds_read2st64_b32 v[8:9], v145 offset0:48 offset1:56
	ds_read2st64_b32 v[10:11], v145 offset0:64 offset1:72
	ds_read2st64_b32 v[12:13], v145 offset0:80 offset1:88
	ds_read2st64_b32 v[14:15], v145 offset0:96 offset1:104
	ds_read2st64_b32 v[16:17], v145 offset0:112 offset1:120
	ds_read2st64_b32 v[18:19], v145 offset0:128 offset1:136
	ds_read2st64_b32 v[20:21], v145 offset0:144 offset1:152
	ds_read2st64_b32 v[22:23], v145 offset0:160 offset1:168
	ds_read2st64_b32 v[24:25], v145 offset0:176 offset1:184
	ds_read2st64_b32 v[26:27], v145 offset0:192 offset1:200
	ds_read2st64_b32 v[28:29], v145 offset0:208 offset1:216
	ds_read2st64_b32 v[30:31], v145 offset0:224 offset1:232
	ds_read2st64_b32 v[32:33], v145 offset0:240 offset1:248
	s_waitcnt lgkmcnt(4)
	v_cvt_f32_f16_e32 v44, v25
	s_waitcnt lgkmcnt(3)
	v_cvt_f32_f16_e32 v42, v27
	s_waitcnt lgkmcnt(2)
	v_cvt_f32_f16_e32 v40, v29
	s_waitcnt lgkmcnt(1)
	v_cvt_f32_f16_e32 v38, v31
	s_waitcnt lgkmcnt(0)
	v_cvt_f32_f16_e32 v36, v33
	v_cvt_f32_f16_e32 v37, v32
	v_cvt_f32_f16_e32 v39, v30
	v_cvt_f32_f16_e32 v41, v28
	v_cvt_f32_f16_e32 v43, v26
	v_cvt_f32_f16_e32 v45, v24
	v_cvt_f32_f16_e32 v46, v23
	v_cvt_f32_f16_e32 v47, v22
	v_cvt_f32_f16_e32 v48, v21
	v_cvt_f32_f16_e32 v49, v20
	v_cvt_f32_f16_e32 v88, v19
	v_cvt_f32_f16_e32 v89, v18
	v_cvt_f32_f16_e32 v90, v17
	v_cvt_f32_f16_e32 v91, v16
	v_cvt_f32_f16_e32 v92, v15
	v_cvt_f32_f16_e32 v93, v14
	v_cvt_f32_f16_e32 v94, v13
	v_cvt_f32_f16_e32 v95, v12
	v_cvt_f32_f16_e32 v96, v11
	v_cvt_f32_f16_e32 v97, v10
	v_cvt_f32_f16_e32 v98, v9
	v_cvt_f32_f16_e32 v99, v8
	v_cvt_f32_f16_e32 v100, v7
	v_cvt_f32_f16_e32 v101, v6
	v_cvt_f32_f16_e32 v102, v5
	v_cvt_f32_f16_e32 v103, v4
	v_cvt_f32_f16_e32 v104, v3
	v_cvt_f32_f16_e32 v105, v2
	s_and_saveexec_b64 s[0:1], s[6:7]
	s_xor_b64 s[0:1], exec, s[0:1]
	s_cbranch_execz .LBB0_574
	v_sub_f32_e32 v34, 1.0, v36
	v_fma_mix_f32 v33, v34, 0, v33 op_sel:[0,0,1] op_sel_hi:[0,0,1]
	v_sub_f32_e32 v35, 1.0, v37
	v_fma_mix_f32 v32, v35, v33, v32 op_sel:[0,0,1] op_sel_hi:[0,0,1]
	v_mul_f32_e32 v33, v35, v34
	v_sub_f32_e32 v34, 1.0, v38
	v_fma_mix_f32 v31, v34, v32, v31 op_sel:[0,0,1] op_sel_hi:[0,0,1]
	v_mul_f32_e32 v32, v34, v33
	v_sub_f32_e32 v33, 1.0, v39
	v_fma_mix_f32 v30, v33, v31, v30 op_sel:[0,0,1] op_sel_hi:[0,0,1]
	v_mul_f32_e32 v31, v33, v32
	v_sub_f32_e32 v32, 1.0, v40
	v_fma_mix_f32 v29, v32, v30, v29 op_sel:[0,0,1] op_sel_hi:[0,0,1]
	v_mul_f32_e32 v30, v32, v31
	v_sub_f32_e32 v31, 1.0, v41
	v_fma_mix_f32 v28, v31, v29, v28 op_sel:[0,0,1] op_sel_hi:[0,0,1]
	v_mul_f32_e32 v29, v31, v30
	v_sub_f32_e32 v30, 1.0, v42
	v_fma_mix_f32 v27, v30, v28, v27 op_sel:[0,0,1] op_sel_hi:[0,0,1]
	v_mul_f32_e32 v28, v30, v29
	v_sub_f32_e32 v29, 1.0, v43
	v_fma_mix_f32 v26, v29, v27, v26 op_sel:[0,0,1] op_sel_hi:[0,0,1]
	v_mul_f32_e32 v27, v29, v28
	v_sub_f32_e32 v28, 1.0, v44
	v_fma_mix_f32 v25, v28, v26, v25 op_sel:[0,0,1] op_sel_hi:[0,0,1]
	v_mul_f32_e32 v26, v28, v27
	v_sub_f32_e32 v27, 1.0, v45
	v_fma_mix_f32 v24, v27, v25, v24 op_sel:[0,0,1] op_sel_hi:[0,0,1]
	v_mul_f32_e32 v25, v27, v26
	v_sub_f32_e32 v26, 1.0, v46
	v_fma_mix_f32 v23, v26, v24, v23 op_sel:[0,0,1] op_sel_hi:[0,0,1]
	v_mul_f32_e32 v24, v26, v25
	v_sub_f32_e32 v25, 1.0, v47
	v_fma_mix_f32 v22, v25, v23, v22 op_sel:[0,0,1] op_sel_hi:[0,0,1]
	v_mul_f32_e32 v23, v25, v24
	v_sub_f32_e32 v24, 1.0, v48
	v_fma_mix_f32 v21, v24, v22, v21 op_sel:[0,0,1] op_sel_hi:[0,0,1]
	v_mul_f32_e32 v22, v24, v23
	v_sub_f32_e32 v23, 1.0, v49
	v_fma_mix_f32 v20, v23, v21, v20 op_sel:[0,0,1] op_sel_hi:[0,0,1]
	v_mul_f32_e32 v21, v23, v22
	v_sub_f32_e32 v22, 1.0, v88
	v_fma_mix_f32 v19, v22, v20, v19 op_sel:[0,0,1] op_sel_hi:[0,0,1]
	v_mul_f32_e32 v20, v22, v21
	v_sub_f32_e32 v21, 1.0, v89
	v_fma_mix_f32 v18, v21, v19, v18 op_sel:[0,0,1] op_sel_hi:[0,0,1]
	v_mul_f32_e32 v19, v21, v20
	v_sub_f32_e32 v20, 1.0, v90
	v_fma_mix_f32 v17, v20, v18, v17 op_sel:[0,0,1] op_sel_hi:[0,0,1]
	v_mul_f32_e32 v18, v20, v19
	v_sub_f32_e32 v19, 1.0, v91
	v_fma_mix_f32 v16, v19, v17, v16 op_sel:[0,0,1] op_sel_hi:[0,0,1]
	v_mul_f32_e32 v17, v19, v18
	v_sub_f32_e32 v18, 1.0, v92
	v_fma_mix_f32 v15, v18, v16, v15 op_sel:[0,0,1] op_sel_hi:[0,0,1]
	v_mul_f32_e32 v16, v18, v17
	v_sub_f32_e32 v17, 1.0, v93
	v_fma_mix_f32 v14, v17, v15, v14 op_sel:[0,0,1] op_sel_hi:[0,0,1]
	v_mul_f32_e32 v15, v17, v16
	v_sub_f32_e32 v16, 1.0, v94
	v_fma_mix_f32 v13, v16, v14, v13 op_sel:[0,0,1] op_sel_hi:[0,0,1]
	v_mul_f32_e32 v14, v16, v15
	v_sub_f32_e32 v15, 1.0, v95
	v_fma_mix_f32 v12, v15, v13, v12 op_sel:[0,0,1] op_sel_hi:[0,0,1]
	v_mul_f32_e32 v13, v15, v14
	v_sub_f32_e32 v14, 1.0, v96
	v_fma_mix_f32 v11, v14, v12, v11 op_sel:[0,0,1] op_sel_hi:[0,0,1]
	v_mul_f32_e32 v12, v14, v13
	v_sub_f32_e32 v13, 1.0, v97
	v_fma_mix_f32 v10, v13, v11, v10 op_sel:[0,0,1] op_sel_hi:[0,0,1]
	v_mul_f32_e32 v11, v13, v12
	v_sub_f32_e32 v12, 1.0, v98
	v_fma_mix_f32 v9, v12, v10, v9 op_sel:[0,0,1] op_sel_hi:[0,0,1]
	v_mul_f32_e32 v10, v12, v11
	v_sub_f32_e32 v11, 1.0, v99
	v_fma_mix_f32 v8, v11, v9, v8 op_sel:[0,0,1] op_sel_hi:[0,0,1]
	v_mul_f32_e32 v9, v11, v10
	v_sub_f32_e32 v10, 1.0, v100
	v_fma_mix_f32 v7, v10, v8, v7 op_sel:[0,0,1] op_sel_hi:[0,0,1]
	v_mul_f32_e32 v8, v10, v9
	v_sub_f32_e32 v9, 1.0, v101
	v_fma_mix_f32 v6, v9, v7, v6 op_sel:[0,0,1] op_sel_hi:[0,0,1]
	v_mul_f32_e32 v7, v9, v8
	v_sub_f32_e32 v8, 1.0, v102
	v_fma_mix_f32 v5, v8, v6, v5 op_sel:[0,0,1] op_sel_hi:[0,0,1]
	v_mul_f32_e32 v6, v8, v7
	v_sub_f32_e32 v7, 1.0, v103
	v_fma_mix_f32 v4, v7, v5, v4 op_sel:[0,0,1] op_sel_hi:[0,0,1]
	v_mul_f32_e32 v5, v7, v6
	v_sub_f32_e32 v6, 1.0, v104
	v_fma_mix_f32 v3, v6, v4, v3 op_sel:[0,0,1] op_sel_hi:[0,0,1]
	v_mul_f32_e32 v4, v6, v5
	v_sub_f32_e32 v5, 1.0, v105
	v_fma_mix_f32 v2, v5, v3, v2 op_sel:[0,0,1] op_sel_hi:[0,0,1]
	v_mul_f32_e32 v34, v5, v4
	v_add_f32_e32 v35, 0, v2
